# K-loops: the early wave group (waves 0-3) skips the pre-barrier lgkmcnt(0) wait in load phases (only the late group's wait is needed for the LDS ring WAR); on top of DMA-first phases 2/4
# baseline (speedup 1.0000x reference)
.LBB0_511:
	s_add_i32 s62, s30, 2
	s_add_u32 s63, s28, 0x80
	s_addc_u32 s31, s29, 0
	s_add_i32 s66, 0, 0x10000
	s_cmp_eq_u32 s54, s30
	s_cselect_b32 s31, s7, s31
	s_cselect_b32 s30, s6, s63
	v_add_u32_e32 v156, s66, v141
	s_cselect_b32 s65, s27, s61
	s_cselect_b32 s64, s26, s60
	s_add_i32 s63, 0, 0x14000
	ds_read_b128 v[144:147], v156
	ds_read_b128 v[148:151], v156 offset:1024
	ds_read_b128 v[152:155], v156 offset:2048
	ds_read_b128 v[160:163], v156 offset:3072
	v_add_u32_e32 v156, s63, v141
	ds_read_b128 v[164:167], v156
	ds_read_b128 v[168:171], v156 offset:1024
	ds_read_b128 v[172:175], v156 offset:2048
	ds_read_b128 v[176:179], v156 offset:3072
	v_lshl_add_u64 v[156:157], s[28:29], 0, v[136:137]
	s_add_i32 m0, s47, 0xc000
	ds_read_b128 v[180:183], v143
	ds_read_b128 v[184:187], v143 offset:1024
	ds_read_b128 v[188:191], v143 offset:2048
	ds_read_b128 v[192:195], v143 offset:3072
	ds_read_b128 v[214:217], v143 offset:4096
	ds_read_b128 v[218:221], v143 offset:5120
	ds_read_b128 v[222:225], v143 offset:6144
	ds_read_b128 v[226:229], v143 offset:7168
	global_load_lds_dwordx4 v[156:157], off
	v_lshl_add_u64 v[156:157], s[28:29], 0, v[138:139]
	s_add_i32 m0, s47, 0xe000
	s_nop 0
	global_load_lds_dwordx4 v[156:157], off
	s_waitcnt vmcnt(8)
	s_cmp_lg_u32 s24, 0
	s_cbranch_scc1 .Lew_511_8658
	s_waitcnt lgkmcnt(0)
.Lew_511_8658:
	s_barrier
	s_setprio 1
	s_waitcnt lgkmcnt(0)
	v_mfma_f32_16x16x32_bf16 v[122:125], v[144:147], v[180:183], v[122:125]
	v_mfma_f32_16x16x32_bf16 v[118:121], v[152:155], v[180:183], v[118:121]
	v_mfma_f32_16x16x32_bf16 v[110:113], v[144:147], v[188:191], v[110:113]
	v_mfma_f32_16x16x32_bf16 v[102:105], v[152:155], v[188:191], v[102:105]
	v_mfma_f32_16x16x32_bf16 v[94:97], v[144:147], v[214:217], v[94:97]
	v_mfma_f32_16x16x32_bf16 v[84:87], v[152:155], v[214:217], v[84:87]
	v_mfma_f32_16x16x32_bf16 v[76:79], v[144:147], v[222:225], v[76:79]
	v_mfma_f32_16x16x32_bf16 v[68:71], v[152:155], v[222:225], v[68:71]
	v_mfma_f32_16x16x32_bf16 v[122:125], v[148:151], v[184:187], v[122:125]
	v_mfma_f32_16x16x32_bf16 v[118:121], v[160:163], v[184:187], v[118:121]
	v_mfma_f32_16x16x32_bf16 v[110:113], v[148:151], v[192:195], v[110:113]
	v_mfma_f32_16x16x32_bf16 v[102:105], v[160:163], v[192:195], v[102:105]
	v_mfma_f32_16x16x32_bf16 v[94:97], v[148:151], v[218:221], v[94:97]
	v_mfma_f32_16x16x32_bf16 v[84:87], v[160:163], v[218:221], v[84:87]
	v_mfma_f32_16x16x32_bf16 v[76:79], v[148:151], v[226:229], v[76:79]
	v_mfma_f32_16x16x32_bf16 v[68:71], v[160:163], v[226:229], v[68:71]
	s_setprio 0
	s_setprio 1
	v_mfma_f32_16x16x32_bf16 v[126:129], v[164:167], v[180:183], v[126:129]
	v_mfma_f32_16x16x32_bf16 v[114:117], v[172:175], v[180:183], v[114:117]
	v_mfma_f32_16x16x32_bf16 v[106:109], v[164:167], v[188:191], v[106:109]
	v_mfma_f32_16x16x32_bf16 v[98:101], v[172:175], v[188:191], v[98:101]
	v_mfma_f32_16x16x32_bf16 v[88:91], v[164:167], v[214:217], v[88:91]
	v_mfma_f32_16x16x32_bf16 v[80:83], v[172:175], v[214:217], v[80:83]
	v_mfma_f32_16x16x32_bf16 v[72:75], v[164:167], v[222:225], v[72:75]
	v_mfma_f32_16x16x32_bf16 v[64:67], v[172:175], v[222:225], v[64:67]
	v_mfma_f32_16x16x32_bf16 v[126:129], v[168:171], v[184:187], v[126:129]
	v_mfma_f32_16x16x32_bf16 v[114:117], v[176:179], v[184:187], v[114:117]
	v_mfma_f32_16x16x32_bf16 v[106:109], v[168:171], v[192:195], v[106:109]
	v_mfma_f32_16x16x32_bf16 v[98:101], v[176:179], v[192:195], v[98:101]
	v_mfma_f32_16x16x32_bf16 v[88:91], v[168:171], v[218:221], v[88:91]
	v_mfma_f32_16x16x32_bf16 v[80:83], v[176:179], v[218:221], v[80:83]
	v_mfma_f32_16x16x32_bf16 v[72:75], v[168:171], v[226:229], v[72:75]
	v_mfma_f32_16x16x32_bf16 v[64:67], v[176:179], v[226:229], v[64:67]
	s_setprio 0
	s_barrier
	s_add_i32 s66, s66, s44
	v_lshl_add_u64 v[156:157], s[64:65], 0, v[92:93]
	s_mov_b32 m0, s66
	global_load_lds_dwordx4 v[156:157], off
	s_add_i32 m0, s66, 0x2000
	v_lshl_add_u64 v[230:231], s[64:65], 0, v[134:135]
	s_add_u32 s64, s64, s10
	s_addc_u32 s65, s65, s11
	s_add_i32 s63, s63, s44
	global_load_lds_dwordx4 v[230:231], off
	v_lshl_add_u64 v[232:233], s[64:65], 0, v[92:93]
	s_mov_b32 m0, s63
	v_lshl_add_u64 v[234:235], s[64:65], 0, v[134:135]
	global_load_lds_dwordx4 v[232:233], off
	s_add_i32 m0, s63, 0x2000
	v_lshl_add_u64 v[236:237], s[30:31], 0, v[130:131]
	global_load_lds_dwordx4 v[234:235], off
	s_mov_b32 m0, s47
	v_lshl_add_u64 v[238:239], s[30:31], 0, v[132:133]
	global_load_lds_dwordx4 v[236:237], off
	s_mov_b32 m0, s48
	s_nop 0
	global_load_lds_dwordx4 v[238:239], off
	ds_read_b128 v[180:183], v143 offset:16384
	ds_read_b128 v[184:187], v143 offset:17408
	ds_read_b128 v[188:191], v143 offset:18432
	ds_read_b128 v[192:195], v143 offset:19456
	ds_read_b128 v[214:217], v143 offset:20480
	ds_read_b128 v[218:221], v143 offset:21504
	ds_read_b128 v[222:225], v143 offset:22528
	ds_read_b128 v[226:229], v143 offset:23552
	s_waitcnt vmcnt(8)
	s_cmp_lg_u32 s24, 0
	s_cbranch_scc1 .Lew_511_8735
	s_waitcnt lgkmcnt(0)
.Lew_511_8735:
	s_barrier
	s_setprio 1
	s_waitcnt lgkmcnt(0)
	v_mfma_f32_16x16x32_bf16 v[60:63], v[144:147], v[180:183], v[60:63]
	v_mfma_f32_16x16x32_bf16 v[52:55], v[152:155], v[180:183], v[52:55]
	v_mfma_f32_16x16x32_bf16 v[44:47], v[144:147], v[188:191], v[44:47]
	v_mfma_f32_16x16x32_bf16 v[36:39], v[152:155], v[188:191], v[36:39]
	v_mfma_f32_16x16x32_bf16 v[28:31], v[144:147], v[214:217], v[28:31]
	v_mfma_f32_16x16x32_bf16 v[20:23], v[152:155], v[214:217], v[20:23]
	v_mfma_f32_16x16x32_bf16 v[12:15], v[144:147], v[222:225], v[12:15]
	v_mfma_f32_16x16x32_bf16 v[4:7], v[152:155], v[222:225], v[4:7]
	v_mfma_f32_16x16x32_bf16 v[60:63], v[148:151], v[184:187], v[60:63]
	v_mfma_f32_16x16x32_bf16 v[52:55], v[160:163], v[184:187], v[52:55]
	v_mfma_f32_16x16x32_bf16 v[44:47], v[148:151], v[192:195], v[44:47]
	v_mfma_f32_16x16x32_bf16 v[36:39], v[160:163], v[192:195], v[36:39]
	v_mfma_f32_16x16x32_bf16 v[28:31], v[148:151], v[218:221], v[28:31]
	v_mfma_f32_16x16x32_bf16 v[20:23], v[160:163], v[218:221], v[20:23]
	v_mfma_f32_16x16x32_bf16 v[12:15], v[148:151], v[226:229], v[12:15]
	v_mfma_f32_16x16x32_bf16 v[4:7], v[160:163], v[226:229], v[4:7]
	s_setprio 0
	s_setprio 1
	v_mfma_f32_16x16x32_bf16 v[56:59], v[164:167], v[180:183], v[56:59]
	v_mfma_f32_16x16x32_bf16 v[48:51], v[172:175], v[180:183], v[48:51]
	v_mfma_f32_16x16x32_bf16 v[40:43], v[164:167], v[188:191], v[40:43]
	v_mfma_f32_16x16x32_bf16 v[32:35], v[172:175], v[188:191], v[32:35]
	v_mfma_f32_16x16x32_bf16 v[24:27], v[164:167], v[214:217], v[24:27]
	v_mfma_f32_16x16x32_bf16 v[16:19], v[172:175], v[214:217], v[16:19]
	v_mfma_f32_16x16x32_bf16 v[8:11], v[164:167], v[222:225], v[8:11]
	v_mfma_f32_16x16x32_bf16 v[0:3], v[172:175], v[222:225], v[0:3]
	v_mfma_f32_16x16x32_bf16 v[56:59], v[168:171], v[184:187], v[56:59]
	v_mfma_f32_16x16x32_bf16 v[48:51], v[176:179], v[184:187], v[48:51]
	v_mfma_f32_16x16x32_bf16 v[40:43], v[168:171], v[192:195], v[40:43]
	v_mfma_f32_16x16x32_bf16 v[32:35], v[176:179], v[192:195], v[32:35]
	v_mfma_f32_16x16x32_bf16 v[24:27], v[168:171], v[218:221], v[24:27]
	v_mfma_f32_16x16x32_bf16 v[16:19], v[176:179], v[218:221], v[16:19]
	v_mfma_f32_16x16x32_bf16 v[8:11], v[168:171], v[226:229], v[8:11]
	v_mfma_f32_16x16x32_bf16 v[0:3], v[176:179], v[226:229], v[0:3]
	s_setprio 0
	s_barrier
	s_add_i32 s63, 0, 0x18000
	v_add_u32_e32 v159, s63, v141
	s_add_i32 s64, 0, 0x1c000
	ds_read_b128 v[144:147], v159
	ds_read_b128 v[148:151], v159 offset:1024
	ds_read_b128 v[152:155], v159 offset:2048
	ds_read_b128 v[160:163], v159 offset:3072
	v_add_u32_e32 v159, s64, v141
	ds_read_b128 v[164:167], v159
	ds_read_b128 v[168:171], v159 offset:1024
	ds_read_b128 v[172:175], v159 offset:2048
	ds_read_b128 v[176:179], v159 offset:3072
	s_add_u32 s30, s30, s14
	s_addc_u32 s31, s31, s15
	s_mov_b32 m0, s49
	v_lshl_add_u64 v[240:241], s[30:31], 0, v[130:131]
	ds_read_b128 v[180:183], v143 offset:32768
	ds_read_b128 v[184:187], v143 offset:33792
	ds_read_b128 v[188:191], v143 offset:34816
	ds_read_b128 v[192:195], v143 offset:35840
	ds_read_b128 v[214:217], v143 offset:36864
	ds_read_b128 v[218:221], v143 offset:37888
	ds_read_b128 v[222:225], v143 offset:38912
	ds_read_b128 v[226:229], v143 offset:39936
	global_load_lds_dwordx4 v[240:241], off
	v_lshl_add_u64 v[240:241], s[30:31], 0, v[132:133]
	s_mov_b32 m0, s50
	s_nop 0
	global_load_lds_dwordx4 v[240:241], off
	s_waitcnt vmcnt(8)
	s_cmp_lg_u32 s24, 0
	s_cbranch_scc1 .Lew_511_8811
	s_waitcnt lgkmcnt(0)
.Lew_511_8811:
	s_barrier
	s_setprio 1
	s_waitcnt lgkmcnt(0)
	v_mfma_f32_16x16x32_bf16 v[122:125], v[144:147], v[180:183], v[122:125]
	v_mfma_f32_16x16x32_bf16 v[118:121], v[152:155], v[180:183], v[118:121]
	v_mfma_f32_16x16x32_bf16 v[110:113], v[144:147], v[188:191], v[110:113]
	v_mfma_f32_16x16x32_bf16 v[102:105], v[152:155], v[188:191], v[102:105]
	v_mfma_f32_16x16x32_bf16 v[94:97], v[144:147], v[214:217], v[94:97]
	v_mfma_f32_16x16x32_bf16 v[84:87], v[152:155], v[214:217], v[84:87]
	v_mfma_f32_16x16x32_bf16 v[76:79], v[144:147], v[222:225], v[76:79]
	v_mfma_f32_16x16x32_bf16 v[68:71], v[152:155], v[222:225], v[68:71]
	v_mfma_f32_16x16x32_bf16 v[122:125], v[148:151], v[184:187], v[122:125]
	v_mfma_f32_16x16x32_bf16 v[118:121], v[160:163], v[184:187], v[118:121]
	v_mfma_f32_16x16x32_bf16 v[110:113], v[148:151], v[192:195], v[110:113]
	v_mfma_f32_16x16x32_bf16 v[102:105], v[160:163], v[192:195], v[102:105]
	v_mfma_f32_16x16x32_bf16 v[94:97], v[148:151], v[218:221], v[94:97]
	v_mfma_f32_16x16x32_bf16 v[84:87], v[160:163], v[218:221], v[84:87]
	v_mfma_f32_16x16x32_bf16 v[76:79], v[148:151], v[226:229], v[76:79]
	v_mfma_f32_16x16x32_bf16 v[68:71], v[160:163], v[226:229], v[68:71]
	s_setprio 0
	s_setprio 1
	v_mfma_f32_16x16x32_bf16 v[126:129], v[164:167], v[180:183], v[126:129]
	v_mfma_f32_16x16x32_bf16 v[114:117], v[172:175], v[180:183], v[114:117]
	v_mfma_f32_16x16x32_bf16 v[106:109], v[164:167], v[188:191], v[106:109]
	v_mfma_f32_16x16x32_bf16 v[98:101], v[172:175], v[188:191], v[98:101]
	v_mfma_f32_16x16x32_bf16 v[88:91], v[164:167], v[214:217], v[88:91]
	v_mfma_f32_16x16x32_bf16 v[80:83], v[172:175], v[214:217], v[80:83]
	v_mfma_f32_16x16x32_bf16 v[72:75], v[164:167], v[222:225], v[72:75]
	v_mfma_f32_16x16x32_bf16 v[64:67], v[172:175], v[222:225], v[64:67]
	v_mfma_f32_16x16x32_bf16 v[126:129], v[168:171], v[184:187], v[126:129]
	v_mfma_f32_16x16x32_bf16 v[114:117], v[176:179], v[184:187], v[114:117]
	v_mfma_f32_16x16x32_bf16 v[106:109], v[168:171], v[192:195], v[106:109]
	v_mfma_f32_16x16x32_bf16 v[98:101], v[176:179], v[192:195], v[98:101]
	v_mfma_f32_16x16x32_bf16 v[88:91], v[168:171], v[218:221], v[88:91]
	v_mfma_f32_16x16x32_bf16 v[80:83], v[176:179], v[218:221], v[80:83]
	v_mfma_f32_16x16x32_bf16 v[72:75], v[168:171], v[226:229], v[72:75]
	v_mfma_f32_16x16x32_bf16 v[64:67], v[176:179], v[226:229], v[64:67]
	s_setprio 0
	s_barrier
	s_add_i32 s30, s63, s44
	v_lshl_add_u64 v[156:157], v[156:157], 0, s[80:81]
	s_mov_b32 m0, s30
	global_load_lds_dwordx4 v[156:157], off
	v_lshl_add_u64 v[156:157], v[230:231], 0, s[80:81]
	s_add_i32 m0, s30, 0x2000
	s_add_i32 s30, s64, s44
	global_load_lds_dwordx4 v[156:157], off
	v_lshl_add_u64 v[156:157], v[232:233], 0, s[80:81]
	s_mov_b32 m0, s30
	s_nop 0
	global_load_lds_dwordx4 v[156:157], off
	v_lshl_add_u64 v[156:157], v[234:235], 0, s[80:81]
	s_add_i32 m0, s30, 0x2000
	s_nop 0
	global_load_lds_dwordx4 v[156:157], off
	v_lshl_add_u64 v[156:157], v[236:237], 0, s[80:81]
	s_mov_b32 m0, s51
	s_nop 0
	global_load_lds_dwordx4 v[156:157], off
	v_lshl_add_u64 v[156:157], v[238:239], 0, s[80:81]
	s_mov_b32 m0, s52
	s_nop 0
	global_load_lds_dwordx4 v[156:157], off
	ds_read_b128 v[180:183], v143 offset:49152
	ds_read_b128 v[184:187], v143 offset:50176
	ds_read_b128 v[188:191], v143 offset:51200
	ds_read_b128 v[192:195], v143 offset:52224
	ds_read_b128 v[214:217], v143 offset:53248
	ds_read_b128 v[218:221], v143 offset:54272
	ds_read_b128 v[222:225], v143 offset:55296
	ds_read_b128 v[226:229], v143 offset:56320
	s_waitcnt vmcnt(8)
	s_cmp_lg_u32 s24, 0
	s_cbranch_scc1 .Lew_511_8889
	s_waitcnt lgkmcnt(0)
.Lew_511_8889:
	s_barrier
	s_setprio 1
	s_waitcnt lgkmcnt(0)
	v_mfma_f32_16x16x32_bf16 v[60:63], v[144:147], v[180:183], v[60:63]
	v_mfma_f32_16x16x32_bf16 v[52:55], v[152:155], v[180:183], v[52:55]
	v_mfma_f32_16x16x32_bf16 v[44:47], v[144:147], v[188:191], v[44:47]
	v_mfma_f32_16x16x32_bf16 v[36:39], v[152:155], v[188:191], v[36:39]
	v_mfma_f32_16x16x32_bf16 v[28:31], v[144:147], v[214:217], v[28:31]
	v_mfma_f32_16x16x32_bf16 v[20:23], v[152:155], v[214:217], v[20:23]
	v_mfma_f32_16x16x32_bf16 v[12:15], v[144:147], v[222:225], v[12:15]
	v_mfma_f32_16x16x32_bf16 v[4:7], v[152:155], v[222:225], v[4:7]
	v_mfma_f32_16x16x32_bf16 v[60:63], v[148:151], v[184:187], v[60:63]
	v_mfma_f32_16x16x32_bf16 v[52:55], v[160:163], v[184:187], v[52:55]
	v_mfma_f32_16x16x32_bf16 v[44:47], v[148:151], v[192:195], v[44:47]
	v_mfma_f32_16x16x32_bf16 v[36:39], v[160:163], v[192:195], v[36:39]
	v_mfma_f32_16x16x32_bf16 v[28:31], v[148:151], v[218:221], v[28:31]
	v_mfma_f32_16x16x32_bf16 v[20:23], v[160:163], v[218:221], v[20:23]
	v_mfma_f32_16x16x32_bf16 v[12:15], v[148:151], v[226:229], v[12:15]
	v_mfma_f32_16x16x32_bf16 v[4:7], v[160:163], v[226:229], v[4:7]
	s_setprio 0
	s_setprio 1
	v_mfma_f32_16x16x32_bf16 v[56:59], v[164:167], v[180:183], v[56:59]
	v_mfma_f32_16x16x32_bf16 v[48:51], v[172:175], v[180:183], v[48:51]
	v_mfma_f32_16x16x32_bf16 v[40:43], v[164:167], v[188:191], v[40:43]
	v_mfma_f32_16x16x32_bf16 v[32:35], v[172:175], v[188:191], v[32:35]
	v_mfma_f32_16x16x32_bf16 v[24:27], v[164:167], v[214:217], v[24:27]
	v_mfma_f32_16x16x32_bf16 v[16:19], v[172:175], v[214:217], v[16:19]
	v_mfma_f32_16x16x32_bf16 v[8:11], v[164:167], v[222:225], v[8:11]
	v_mfma_f32_16x16x32_bf16 v[0:3], v[172:175], v[222:225], v[0:3]
	v_mfma_f32_16x16x32_bf16 v[56:59], v[168:171], v[184:187], v[56:59]
	v_mfma_f32_16x16x32_bf16 v[48:51], v[176:179], v[184:187], v[48:51]
	v_mfma_f32_16x16x32_bf16 v[40:43], v[168:171], v[192:195], v[40:43]
	v_mfma_f32_16x16x32_bf16 v[32:35], v[176:179], v[192:195], v[32:35]
	v_mfma_f32_16x16x32_bf16 v[24:27], v[168:171], v[218:221], v[24:27]
	v_mfma_f32_16x16x32_bf16 v[16:19], v[176:179], v[218:221], v[16:19]
	v_mfma_f32_16x16x32_bf16 v[8:11], v[168:171], v[226:229], v[8:11]
	v_mfma_f32_16x16x32_bf16 v[0:3], v[176:179], v[226:229], v[0:3]
	s_setprio 0
	s_barrier
	s_add_u32 s28, s28, 0x100
	s_addc_u32 s29, s29, 0
	s_add_u32 s60, s60, 0x100
	s_addc_u32 s61, s61, 0
	s_cmp_ge_i32 s62, s53
	s_mov_b32 s30, s62
	s_cbranch_scc0 .LBB0_511

.LBB0_596:
	s_add_i32 s63, s30, 2
	s_add_u32 s64, s28, 0x80
	s_addc_u32 s31, s29, 0
	s_add_i32 s66, 0, 0x10000
	s_cmp_eq_u32 s55, s30
	s_cselect_b32 s31, s7, s31
	s_cselect_b32 s30, s6, s64
	s_cselect_b32 s65, s27, s62
	s_cselect_b32 s64, s26, s61
	s_add_i32 s67, 0, 0x14000
	v_add_u32_e32 v152, s66, v164
	v_add_u32_e32 v156, s67, v164
	ds_read_b128 v[140:143], v152
	ds_read_b128 v[144:147], v152 offset:1024
	ds_read_b128 v[148:151], v152 offset:2048
	ds_read_b128 v[152:155], v152 offset:3072
	ds_read_b128 v[160:163], v156
	ds_read_b128 v[168:171], v156 offset:1024
	ds_read_b128 v[172:175], v156 offset:2048
	ds_read_b128 v[176:179], v156 offset:3072
	v_lshl_add_u64 v[156:157], s[28:29], 0, v[136:137]
	s_add_i32 m0, s46, 0xc000
	ds_read_b128 v[180:183], v166
	ds_read_b128 v[184:187], v166 offset:1024
	ds_read_b128 v[188:191], v166 offset:2048
	ds_read_b128 v[192:195], v166 offset:3072
	ds_read_b128 v[214:217], v166 offset:4096
	ds_read_b128 v[218:221], v166 offset:5120
	ds_read_b128 v[222:225], v166 offset:6144
	ds_read_b128 v[226:229], v166 offset:7168
	global_load_lds_dwordx4 v[156:157], off
	v_lshl_add_u64 v[156:157], s[28:29], 0, v[138:139]
	s_add_i32 m0, s46, 0xe000
	s_nop 0
	global_load_lds_dwordx4 v[156:157], off
	s_waitcnt vmcnt(8)
	s_cmp_lg_u32 s24, 0
	s_cbranch_scc1 .Lew_596_10204
	s_waitcnt lgkmcnt(0)
.Lew_596_10204:
	s_barrier
	s_setprio 1
	s_waitcnt lgkmcnt(0)
	v_mfma_f32_16x16x32_bf16 v[126:129], v[140:143], v[180:183], v[126:129]
	v_mfma_f32_16x16x32_bf16 v[122:125], v[148:151], v[180:183], v[122:125]
	v_mfma_f32_16x16x32_bf16 v[110:113], v[140:143], v[188:191], v[110:113]
	v_mfma_f32_16x16x32_bf16 v[106:109], v[148:151], v[188:191], v[106:109]
	v_mfma_f32_16x16x32_bf16 v[94:97], v[140:143], v[214:217], v[94:97]
	v_mfma_f32_16x16x32_bf16 v[88:91], v[148:151], v[214:217], v[88:91]
	v_mfma_f32_16x16x32_bf16 v[76:79], v[140:143], v[222:225], v[76:79]
	v_mfma_f32_16x16x32_bf16 v[72:75], v[148:151], v[222:225], v[72:75]
	v_mfma_f32_16x16x32_bf16 v[126:129], v[144:147], v[184:187], v[126:129]
	v_mfma_f32_16x16x32_bf16 v[122:125], v[152:155], v[184:187], v[122:125]
	v_mfma_f32_16x16x32_bf16 v[110:113], v[144:147], v[192:195], v[110:113]
	v_mfma_f32_16x16x32_bf16 v[106:109], v[152:155], v[192:195], v[106:109]
	v_mfma_f32_16x16x32_bf16 v[94:97], v[144:147], v[218:221], v[94:97]
	v_mfma_f32_16x16x32_bf16 v[88:91], v[152:155], v[218:221], v[88:91]
	v_mfma_f32_16x16x32_bf16 v[76:79], v[144:147], v[226:229], v[76:79]
	v_mfma_f32_16x16x32_bf16 v[72:75], v[152:155], v[226:229], v[72:75]
	s_setprio 0
	s_setprio 1
	v_mfma_f32_16x16x32_bf16 v[118:121], v[160:163], v[180:183], v[118:121]
	v_mfma_f32_16x16x32_bf16 v[114:117], v[172:175], v[180:183], v[114:117]
	v_mfma_f32_16x16x32_bf16 v[102:105], v[160:163], v[188:191], v[102:105]
	v_mfma_f32_16x16x32_bf16 v[98:101], v[172:175], v[188:191], v[98:101]
	v_mfma_f32_16x16x32_bf16 v[84:87], v[160:163], v[214:217], v[84:87]
	v_mfma_f32_16x16x32_bf16 v[80:83], v[172:175], v[214:217], v[80:83]
	v_mfma_f32_16x16x32_bf16 v[68:71], v[160:163], v[222:225], v[68:71]
	v_mfma_f32_16x16x32_bf16 v[64:67], v[172:175], v[222:225], v[64:67]
	v_mfma_f32_16x16x32_bf16 v[118:121], v[168:171], v[184:187], v[118:121]
	v_mfma_f32_16x16x32_bf16 v[114:117], v[176:179], v[184:187], v[114:117]
	v_mfma_f32_16x16x32_bf16 v[102:105], v[168:171], v[192:195], v[102:105]
	v_mfma_f32_16x16x32_bf16 v[98:101], v[176:179], v[192:195], v[98:101]
	v_mfma_f32_16x16x32_bf16 v[84:87], v[168:171], v[218:221], v[84:87]
	v_mfma_f32_16x16x32_bf16 v[80:83], v[176:179], v[218:221], v[80:83]
	v_mfma_f32_16x16x32_bf16 v[68:71], v[168:171], v[226:229], v[68:71]
	v_mfma_f32_16x16x32_bf16 v[64:67], v[176:179], v[226:229], v[64:67]
	s_setprio 0
	s_barrier
	s_add_i32 s66, s66, s41
	v_lshl_add_u64 v[156:157], s[64:65], 0, v[92:93]
	s_mov_b32 m0, s66
	global_load_lds_dwordx4 v[156:157], off
	s_add_i32 m0, s66, 0x2000
	v_lshl_add_u64 v[230:231], s[64:65], 0, v[134:135]
	s_add_u32 s64, s64, s10
	s_addc_u32 s65, s65, s11
	s_add_i32 s66, s67, s41
	global_load_lds_dwordx4 v[230:231], off
	v_lshl_add_u64 v[232:233], s[64:65], 0, v[92:93]
	s_mov_b32 m0, s66
	v_lshl_add_u64 v[234:235], s[64:65], 0, v[134:135]
	global_load_lds_dwordx4 v[232:233], off
	s_add_i32 m0, s66, 0x2000
	v_lshl_add_u64 v[236:237], s[30:31], 0, v[130:131]
	global_load_lds_dwordx4 v[234:235], off
	s_mov_b32 m0, s46
	v_lshl_add_u64 v[238:239], s[30:31], 0, v[132:133]
	global_load_lds_dwordx4 v[236:237], off
	s_mov_b32 m0, s47
	s_nop 0
	global_load_lds_dwordx4 v[238:239], off
	ds_read_b128 v[180:183], v166 offset:16384
	ds_read_b128 v[184:187], v166 offset:17408
	ds_read_b128 v[188:191], v166 offset:18432
	ds_read_b128 v[192:195], v166 offset:19456
	ds_read_b128 v[214:217], v166 offset:20480
	ds_read_b128 v[218:221], v166 offset:21504
	ds_read_b128 v[222:225], v166 offset:22528
	ds_read_b128 v[226:229], v166 offset:23552
	s_waitcnt vmcnt(8)
	s_cmp_lg_u32 s24, 0
	s_cbranch_scc1 .Lew_596_10281
	s_waitcnt lgkmcnt(0)
.Lew_596_10281:
	s_barrier
	s_setprio 1
	s_waitcnt lgkmcnt(0)
	v_mfma_f32_16x16x32_bf16 v[60:63], v[140:143], v[180:183], v[60:63]
	v_mfma_f32_16x16x32_bf16 v[56:59], v[148:151], v[180:183], v[56:59]
	v_mfma_f32_16x16x32_bf16 v[44:47], v[140:143], v[188:191], v[44:47]
	v_mfma_f32_16x16x32_bf16 v[40:43], v[148:151], v[188:191], v[40:43]
	v_mfma_f32_16x16x32_bf16 v[28:31], v[140:143], v[214:217], v[28:31]
	v_mfma_f32_16x16x32_bf16 v[24:27], v[148:151], v[214:217], v[24:27]
	v_mfma_f32_16x16x32_bf16 v[12:15], v[140:143], v[222:225], v[12:15]
	v_mfma_f32_16x16x32_bf16 v[8:11], v[148:151], v[222:225], v[8:11]
	v_mfma_f32_16x16x32_bf16 v[60:63], v[144:147], v[184:187], v[60:63]
	v_mfma_f32_16x16x32_bf16 v[56:59], v[152:155], v[184:187], v[56:59]
	v_mfma_f32_16x16x32_bf16 v[44:47], v[144:147], v[192:195], v[44:47]
	v_mfma_f32_16x16x32_bf16 v[40:43], v[152:155], v[192:195], v[40:43]
	v_mfma_f32_16x16x32_bf16 v[28:31], v[144:147], v[218:221], v[28:31]
	v_mfma_f32_16x16x32_bf16 v[24:27], v[152:155], v[218:221], v[24:27]
	v_mfma_f32_16x16x32_bf16 v[12:15], v[144:147], v[226:229], v[12:15]
	v_mfma_f32_16x16x32_bf16 v[8:11], v[152:155], v[226:229], v[8:11]
	s_setprio 0
	s_setprio 1
	v_mfma_f32_16x16x32_bf16 v[52:55], v[160:163], v[180:183], v[52:55]
	v_mfma_f32_16x16x32_bf16 v[48:51], v[172:175], v[180:183], v[48:51]
	v_mfma_f32_16x16x32_bf16 v[36:39], v[160:163], v[188:191], v[36:39]
	v_mfma_f32_16x16x32_bf16 v[32:35], v[172:175], v[188:191], v[32:35]
	v_mfma_f32_16x16x32_bf16 v[20:23], v[160:163], v[214:217], v[20:23]
	v_mfma_f32_16x16x32_bf16 v[16:19], v[172:175], v[214:217], v[16:19]
	v_mfma_f32_16x16x32_bf16 v[4:7], v[160:163], v[222:225], v[4:7]
	v_mfma_f32_16x16x32_bf16 v[0:3], v[172:175], v[222:225], v[0:3]
	v_mfma_f32_16x16x32_bf16 v[52:55], v[168:171], v[184:187], v[52:55]
	v_mfma_f32_16x16x32_bf16 v[48:51], v[176:179], v[184:187], v[48:51]
	v_mfma_f32_16x16x32_bf16 v[36:39], v[168:171], v[192:195], v[36:39]
	v_mfma_f32_16x16x32_bf16 v[32:35], v[176:179], v[192:195], v[32:35]
	v_mfma_f32_16x16x32_bf16 v[20:23], v[168:171], v[218:221], v[20:23]
	v_mfma_f32_16x16x32_bf16 v[16:19], v[176:179], v[218:221], v[16:19]
	v_mfma_f32_16x16x32_bf16 v[4:7], v[168:171], v[226:229], v[4:7]
	v_mfma_f32_16x16x32_bf16 v[0:3], v[176:179], v[226:229], v[0:3]
	s_setprio 0
	s_barrier
	s_add_i32 s64, 0, 0x18000
	s_add_i32 s65, 0, 0x1c000
	v_add_u32_e32 v152, s64, v164
	v_add_u32_e32 v167, s65, v164
	ds_read_b128 v[140:143], v152
	ds_read_b128 v[144:147], v152 offset:1024
	ds_read_b128 v[148:151], v152 offset:2048
	ds_read_b128 v[152:155], v152 offset:3072
	ds_read_b128 v[160:163], v167
	ds_read_b128 v[168:171], v167 offset:1024
	ds_read_b128 v[172:175], v167 offset:2048
	ds_read_b128 v[176:179], v167 offset:3072
	s_add_u32 s30, s30, s14
	s_addc_u32 s31, s31, s15
	s_mov_b32 m0, s48
	v_lshl_add_u64 v[240:241], s[30:31], 0, v[130:131]
	ds_read_b128 v[180:183], v166 offset:32768
	ds_read_b128 v[184:187], v166 offset:33792
	ds_read_b128 v[188:191], v166 offset:34816
	ds_read_b128 v[192:195], v166 offset:35840
	ds_read_b128 v[214:217], v166 offset:36864
	ds_read_b128 v[218:221], v166 offset:37888
	ds_read_b128 v[222:225], v166 offset:38912
	ds_read_b128 v[226:229], v166 offset:39936
	global_load_lds_dwordx4 v[240:241], off
	v_lshl_add_u64 v[240:241], s[30:31], 0, v[132:133]
	s_mov_b32 m0, s49
	s_nop 0
	global_load_lds_dwordx4 v[240:241], off
	s_waitcnt vmcnt(8)
	s_cmp_lg_u32 s24, 0
	s_cbranch_scc1 .Lew_596_10357
	s_waitcnt lgkmcnt(0)
.Lew_596_10357:
	s_barrier
	s_setprio 1
	s_waitcnt lgkmcnt(0)
	v_mfma_f32_16x16x32_bf16 v[126:129], v[140:143], v[180:183], v[126:129]
	v_mfma_f32_16x16x32_bf16 v[122:125], v[148:151], v[180:183], v[122:125]
	v_mfma_f32_16x16x32_bf16 v[110:113], v[140:143], v[188:191], v[110:113]
	v_mfma_f32_16x16x32_bf16 v[106:109], v[148:151], v[188:191], v[106:109]
	v_mfma_f32_16x16x32_bf16 v[94:97], v[140:143], v[214:217], v[94:97]
	v_mfma_f32_16x16x32_bf16 v[88:91], v[148:151], v[214:217], v[88:91]
	v_mfma_f32_16x16x32_bf16 v[76:79], v[140:143], v[222:225], v[76:79]
	v_mfma_f32_16x16x32_bf16 v[72:75], v[148:151], v[222:225], v[72:75]
	v_mfma_f32_16x16x32_bf16 v[126:129], v[144:147], v[184:187], v[126:129]
	v_mfma_f32_16x16x32_bf16 v[122:125], v[152:155], v[184:187], v[122:125]
	v_mfma_f32_16x16x32_bf16 v[110:113], v[144:147], v[192:195], v[110:113]
	v_mfma_f32_16x16x32_bf16 v[106:109], v[152:155], v[192:195], v[106:109]
	v_mfma_f32_16x16x32_bf16 v[94:97], v[144:147], v[218:221], v[94:97]
	v_mfma_f32_16x16x32_bf16 v[88:91], v[152:155], v[218:221], v[88:91]
	v_mfma_f32_16x16x32_bf16 v[76:79], v[144:147], v[226:229], v[76:79]
	v_mfma_f32_16x16x32_bf16 v[72:75], v[152:155], v[226:229], v[72:75]
	s_setprio 0
	s_setprio 1
	v_mfma_f32_16x16x32_bf16 v[118:121], v[160:163], v[180:183], v[118:121]
	v_mfma_f32_16x16x32_bf16 v[114:117], v[172:175], v[180:183], v[114:117]
	v_mfma_f32_16x16x32_bf16 v[102:105], v[160:163], v[188:191], v[102:105]
	v_mfma_f32_16x16x32_bf16 v[98:101], v[172:175], v[188:191], v[98:101]
	v_mfma_f32_16x16x32_bf16 v[84:87], v[160:163], v[214:217], v[84:87]
	v_mfma_f32_16x16x32_bf16 v[80:83], v[172:175], v[214:217], v[80:83]
	v_mfma_f32_16x16x32_bf16 v[68:71], v[160:163], v[222:225], v[68:71]
	v_mfma_f32_16x16x32_bf16 v[64:67], v[172:175], v[222:225], v[64:67]
	v_mfma_f32_16x16x32_bf16 v[118:121], v[168:171], v[184:187], v[118:121]
	v_mfma_f32_16x16x32_bf16 v[114:117], v[176:179], v[184:187], v[114:117]
	v_mfma_f32_16x16x32_bf16 v[102:105], v[168:171], v[192:195], v[102:105]
	v_mfma_f32_16x16x32_bf16 v[98:101], v[176:179], v[192:195], v[98:101]
	v_mfma_f32_16x16x32_bf16 v[84:87], v[168:171], v[218:221], v[84:87]
	v_mfma_f32_16x16x32_bf16 v[80:83], v[176:179], v[218:221], v[80:83]
	v_mfma_f32_16x16x32_bf16 v[68:71], v[168:171], v[226:229], v[68:71]
	v_mfma_f32_16x16x32_bf16 v[64:67], v[176:179], v[226:229], v[64:67]
	s_setprio 0
	s_barrier
	s_add_i32 s30, s64, s41
	v_lshl_add_u64 v[156:157], v[156:157], 0, s[80:81]
	s_mov_b32 m0, s30
	global_load_lds_dwordx4 v[156:157], off
	v_lshl_add_u64 v[156:157], v[230:231], 0, s[80:81]
	s_add_i32 m0, s30, 0x2000
	s_add_i32 s30, s65, s41
	global_load_lds_dwordx4 v[156:157], off
	v_lshl_add_u64 v[156:157], v[232:233], 0, s[80:81]
	s_mov_b32 m0, s30
	s_nop 0
	global_load_lds_dwordx4 v[156:157], off
	v_lshl_add_u64 v[156:157], v[234:235], 0, s[80:81]
	s_add_i32 m0, s30, 0x2000
	s_nop 0
	global_load_lds_dwordx4 v[156:157], off
	v_lshl_add_u64 v[156:157], v[236:237], 0, s[80:81]
	s_mov_b32 m0, s53
	s_nop 0
	global_load_lds_dwordx4 v[156:157], off
	v_lshl_add_u64 v[156:157], v[238:239], 0, s[80:81]
	s_mov_b32 m0, s54
	s_nop 0
	global_load_lds_dwordx4 v[156:157], off
	ds_read_b128 v[180:183], v166 offset:49152
	ds_read_b128 v[184:187], v166 offset:50176
	ds_read_b128 v[188:191], v166 offset:51200
	ds_read_b128 v[192:195], v166 offset:52224
	ds_read_b128 v[214:217], v166 offset:53248
	ds_read_b128 v[218:221], v166 offset:54272
	ds_read_b128 v[222:225], v166 offset:55296
	ds_read_b128 v[226:229], v166 offset:56320
	s_waitcnt vmcnt(8)
	s_cmp_lg_u32 s24, 0
	s_cbranch_scc1 .Lew_596_10435
	s_waitcnt lgkmcnt(0)
.Lew_596_10435:
	s_barrier
	s_setprio 1
	s_waitcnt lgkmcnt(0)
	v_mfma_f32_16x16x32_bf16 v[60:63], v[140:143], v[180:183], v[60:63]
	v_mfma_f32_16x16x32_bf16 v[56:59], v[148:151], v[180:183], v[56:59]
	v_mfma_f32_16x16x32_bf16 v[44:47], v[140:143], v[188:191], v[44:47]
	v_mfma_f32_16x16x32_bf16 v[40:43], v[148:151], v[188:191], v[40:43]
	v_mfma_f32_16x16x32_bf16 v[28:31], v[140:143], v[214:217], v[28:31]
	v_mfma_f32_16x16x32_bf16 v[24:27], v[148:151], v[214:217], v[24:27]
	v_mfma_f32_16x16x32_bf16 v[12:15], v[140:143], v[222:225], v[12:15]
	v_mfma_f32_16x16x32_bf16 v[8:11], v[148:151], v[222:225], v[8:11]
	v_mfma_f32_16x16x32_bf16 v[60:63], v[144:147], v[184:187], v[60:63]
	v_mfma_f32_16x16x32_bf16 v[56:59], v[152:155], v[184:187], v[56:59]
	v_mfma_f32_16x16x32_bf16 v[44:47], v[144:147], v[192:195], v[44:47]
	v_mfma_f32_16x16x32_bf16 v[40:43], v[152:155], v[192:195], v[40:43]
	v_mfma_f32_16x16x32_bf16 v[28:31], v[144:147], v[218:221], v[28:31]
	v_mfma_f32_16x16x32_bf16 v[24:27], v[152:155], v[218:221], v[24:27]
	v_mfma_f32_16x16x32_bf16 v[12:15], v[144:147], v[226:229], v[12:15]
	v_mfma_f32_16x16x32_bf16 v[8:11], v[152:155], v[226:229], v[8:11]
	s_setprio 0
	s_setprio 1
	v_mfma_f32_16x16x32_bf16 v[52:55], v[160:163], v[180:183], v[52:55]
	v_mfma_f32_16x16x32_bf16 v[48:51], v[172:175], v[180:183], v[48:51]
	v_mfma_f32_16x16x32_bf16 v[36:39], v[160:163], v[188:191], v[36:39]
	v_mfma_f32_16x16x32_bf16 v[32:35], v[172:175], v[188:191], v[32:35]
	v_mfma_f32_16x16x32_bf16 v[20:23], v[160:163], v[214:217], v[20:23]
	v_mfma_f32_16x16x32_bf16 v[16:19], v[172:175], v[214:217], v[16:19]
	v_mfma_f32_16x16x32_bf16 v[4:7], v[160:163], v[222:225], v[4:7]
	v_mfma_f32_16x16x32_bf16 v[0:3], v[172:175], v[222:225], v[0:3]
	v_mfma_f32_16x16x32_bf16 v[52:55], v[168:171], v[184:187], v[52:55]
	v_mfma_f32_16x16x32_bf16 v[48:51], v[176:179], v[184:187], v[48:51]
	v_mfma_f32_16x16x32_bf16 v[36:39], v[168:171], v[192:195], v[36:39]
	v_mfma_f32_16x16x32_bf16 v[32:35], v[176:179], v[192:195], v[32:35]
	v_mfma_f32_16x16x32_bf16 v[20:23], v[168:171], v[218:221], v[20:23]
	v_mfma_f32_16x16x32_bf16 v[16:19], v[176:179], v[218:221], v[16:19]
	v_mfma_f32_16x16x32_bf16 v[4:7], v[168:171], v[226:229], v[4:7]
	v_mfma_f32_16x16x32_bf16 v[0:3], v[176:179], v[226:229], v[0:3]
	s_setprio 0
	s_barrier
	s_add_u32 s28, s28, 0x100
	s_addc_u32 s29, s29, 0
	s_add_u32 s61, s61, 0x100
	s_addc_u32 s62, s62, 0
	s_cmp_ge_i32 s63, s52
	s_mov_b32 s30, s63
	s_cbranch_scc0 .LBB0_596
	s_movk_i32 s67, 0x4000

.LBB0_685:
	s_add_i32 s36, s10, 2
	s_add_u32 s37, s8, 0x80
	s_addc_u32 s11, s9, 0
	s_add_i32 s40, 0, 0x10000
	s_cmp_eq_u32 s71, s10
	s_cselect_b32 s11, s29, s11
	s_cselect_b32 s10, s28, s37
	v_add_u32_e32 v92, s40, v141
	s_cselect_b32 s39, s31, s35
	s_cselect_b32 s38, s30, s34
	s_add_i32 s37, 0, 0x14000
	ds_read_b128 v[152:155], v92
	ds_read_b128 v[160:163], v92 offset:1024
	ds_read_b128 v[164:167], v92 offset:2048
	ds_read_b128 v[168:171], v92 offset:3072
	v_add_u32_e32 v92, s37, v141
	ds_read_b128 v[172:175], v92
	ds_read_b128 v[176:179], v92 offset:1024
	ds_read_b128 v[180:183], v92 offset:2048
	ds_read_b128 v[184:187], v92 offset:3072
	v_lshl_add_u64 v[156:157], s[8:9], 0, v[148:149]
	s_add_i32 m0, s54, 0xc000
	ds_read_b128 v[188:191], v143
	ds_read_b128 v[192:195], v143 offset:1024
	ds_read_b128 v[214:217], v143 offset:2048
	ds_read_b128 v[218:221], v143 offset:3072
	ds_read_b128 v[222:225], v143 offset:4096
	ds_read_b128 v[226:229], v143 offset:5120
	ds_read_b128 v[230:233], v143 offset:6144
	ds_read_b128 v[234:237], v143 offset:7168
	global_load_lds_dwordx4 v[156:157], off
	v_lshl_add_u64 v[156:157], s[8:9], 0, v[150:151]
	s_add_i32 m0, s54, 0xe000
	s_nop 0
	global_load_lds_dwordx4 v[156:157], off
	s_waitcnt vmcnt(8)
	s_cmp_lg_u32 s26, 0
	s_cbranch_scc1 .Lew_685_11755
	s_waitcnt lgkmcnt(0)
.Lew_685_11755:
	s_barrier
	s_setprio 1
	s_waitcnt lgkmcnt(0)
	v_mfma_f32_16x16x32_bf16 v[126:129], v[152:155], v[188:191], v[126:129]
	v_mfma_f32_16x16x32_bf16 v[122:125], v[164:167], v[188:191], v[122:125]
	v_mfma_f32_16x16x32_bf16 v[118:121], v[152:155], v[214:217], v[118:121]
	v_mfma_f32_16x16x32_bf16 v[114:117], v[164:167], v[214:217], v[114:117]
	v_mfma_f32_16x16x32_bf16 v[110:113], v[152:155], v[222:225], v[110:113]
	v_mfma_f32_16x16x32_bf16 v[106:109], v[164:167], v[222:225], v[106:109]
	v_mfma_f32_16x16x32_bf16 v[102:105], v[152:155], v[230:233], v[102:105]
	v_mfma_f32_16x16x32_bf16 v[98:101], v[164:167], v[230:233], v[98:101]
	v_mfma_f32_16x16x32_bf16 v[126:129], v[160:163], v[192:195], v[126:129]
	v_mfma_f32_16x16x32_bf16 v[122:125], v[168:171], v[192:195], v[122:125]
	v_mfma_f32_16x16x32_bf16 v[118:121], v[160:163], v[218:221], v[118:121]
	v_mfma_f32_16x16x32_bf16 v[114:117], v[168:171], v[218:221], v[114:117]
	v_mfma_f32_16x16x32_bf16 v[110:113], v[160:163], v[226:229], v[110:113]
	v_mfma_f32_16x16x32_bf16 v[106:109], v[168:171], v[226:229], v[106:109]
	v_mfma_f32_16x16x32_bf16 v[102:105], v[160:163], v[234:237], v[102:105]
	v_mfma_f32_16x16x32_bf16 v[98:101], v[168:171], v[234:237], v[98:101]
	s_setprio 0
	s_setprio 1
	v_mfma_f32_16x16x32_bf16 v[60:63], v[172:175], v[188:191], v[60:63]
	v_mfma_f32_16x16x32_bf16 v[56:59], v[180:183], v[188:191], v[56:59]
	v_mfma_f32_16x16x32_bf16 v[52:55], v[172:175], v[214:217], v[52:55]
	v_mfma_f32_16x16x32_bf16 v[48:51], v[180:183], v[214:217], v[48:51]
	v_mfma_f32_16x16x32_bf16 v[44:47], v[172:175], v[222:225], v[44:47]
	v_mfma_f32_16x16x32_bf16 v[40:43], v[180:183], v[222:225], v[40:43]
	v_mfma_f32_16x16x32_bf16 v[36:39], v[172:175], v[230:233], v[36:39]
	v_mfma_f32_16x16x32_bf16 v[32:35], v[180:183], v[230:233], v[32:35]
	v_mfma_f32_16x16x32_bf16 v[60:63], v[176:179], v[192:195], v[60:63]
	v_mfma_f32_16x16x32_bf16 v[56:59], v[184:187], v[192:195], v[56:59]
	v_mfma_f32_16x16x32_bf16 v[52:55], v[176:179], v[218:221], v[52:55]
	v_mfma_f32_16x16x32_bf16 v[48:51], v[184:187], v[218:221], v[48:51]
	v_mfma_f32_16x16x32_bf16 v[44:47], v[176:179], v[226:229], v[44:47]
	v_mfma_f32_16x16x32_bf16 v[40:43], v[184:187], v[226:229], v[40:43]
	v_mfma_f32_16x16x32_bf16 v[36:39], v[176:179], v[234:237], v[36:39]
	v_mfma_f32_16x16x32_bf16 v[32:35], v[184:187], v[234:237], v[32:35]
	s_setprio 0
	s_barrier
	s_add_i32 s40, s40, s53
	v_lshl_add_u64 v[156:157], s[38:39], 0, v[132:133]
	s_mov_b32 m0, s40
	global_load_lds_dwordx4 v[156:157], off
	s_add_i32 m0, s40, 0x2000
	v_lshl_add_u64 v[238:239], s[38:39], 0, v[136:137]
	s_add_u32 s38, s38, s12
	s_addc_u32 s39, s39, s13
	s_add_i32 s37, s37, s53
	global_load_lds_dwordx4 v[238:239], off
	v_lshl_add_u64 v[240:241], s[38:39], 0, v[132:133]
	s_mov_b32 m0, s37
	v_lshl_add_u64 v[242:243], s[38:39], 0, v[136:137]
	global_load_lds_dwordx4 v[240:241], off
	s_add_i32 m0, s37, 0x2000
	v_lshl_add_u64 v[244:245], s[10:11], 0, v[130:131]
	global_load_lds_dwordx4 v[242:243], off
	s_mov_b32 m0, s54
	v_lshl_add_u64 v[246:247], s[10:11], 0, v[134:135]
	global_load_lds_dwordx4 v[244:245], off
	s_mov_b32 m0, s55
	s_nop 0
	global_load_lds_dwordx4 v[246:247], off
	ds_read_b128 v[188:191], v143 offset:16384
	ds_read_b128 v[192:195], v143 offset:17408
	ds_read_b128 v[214:217], v143 offset:18432
	ds_read_b128 v[218:221], v143 offset:19456
	ds_read_b128 v[222:225], v143 offset:20480
	ds_read_b128 v[226:229], v143 offset:21504
	ds_read_b128 v[230:233], v143 offset:22528
	ds_read_b128 v[234:237], v143 offset:23552
	s_waitcnt vmcnt(8)
	s_cmp_lg_u32 s26, 0
	s_cbranch_scc1 .Lew_685_11832
	s_waitcnt lgkmcnt(0)
.Lew_685_11832:
	s_barrier
	s_setprio 1
	s_waitcnt lgkmcnt(0)
	v_mfma_f32_16x16x32_bf16 v[94:97], v[152:155], v[188:191], v[94:97]
	v_mfma_f32_16x16x32_bf16 v[88:91], v[164:167], v[188:191], v[88:91]
	v_mfma_f32_16x16x32_bf16 v[84:87], v[152:155], v[214:217], v[84:87]
	v_mfma_f32_16x16x32_bf16 v[80:83], v[164:167], v[214:217], v[80:83]
	v_mfma_f32_16x16x32_bf16 v[76:79], v[152:155], v[222:225], v[76:79]
	v_mfma_f32_16x16x32_bf16 v[72:75], v[164:167], v[222:225], v[72:75]
	v_mfma_f32_16x16x32_bf16 v[68:71], v[152:155], v[230:233], v[68:71]
	v_mfma_f32_16x16x32_bf16 v[64:67], v[164:167], v[230:233], v[64:67]
	v_mfma_f32_16x16x32_bf16 v[94:97], v[160:163], v[192:195], v[94:97]
	v_mfma_f32_16x16x32_bf16 v[88:91], v[168:171], v[192:195], v[88:91]
	v_mfma_f32_16x16x32_bf16 v[84:87], v[160:163], v[218:221], v[84:87]
	v_mfma_f32_16x16x32_bf16 v[80:83], v[168:171], v[218:221], v[80:83]
	v_mfma_f32_16x16x32_bf16 v[76:79], v[160:163], v[226:229], v[76:79]
	v_mfma_f32_16x16x32_bf16 v[72:75], v[168:171], v[226:229], v[72:75]
	v_mfma_f32_16x16x32_bf16 v[68:71], v[160:163], v[234:237], v[68:71]
	v_mfma_f32_16x16x32_bf16 v[64:67], v[168:171], v[234:237], v[64:67]
	s_setprio 0
	s_setprio 1
	v_mfma_f32_16x16x32_bf16 v[28:31], v[172:175], v[188:191], v[28:31]
	v_mfma_f32_16x16x32_bf16 v[24:27], v[180:183], v[188:191], v[24:27]
	v_mfma_f32_16x16x32_bf16 v[20:23], v[172:175], v[214:217], v[20:23]
	v_mfma_f32_16x16x32_bf16 v[16:19], v[180:183], v[214:217], v[16:19]
	v_mfma_f32_16x16x32_bf16 v[12:15], v[172:175], v[222:225], v[12:15]
	v_mfma_f32_16x16x32_bf16 v[8:11], v[180:183], v[222:225], v[8:11]
	v_mfma_f32_16x16x32_bf16 v[4:7], v[172:175], v[230:233], v[4:7]
	v_mfma_f32_16x16x32_bf16 v[0:3], v[180:183], v[230:233], v[0:3]
	v_mfma_f32_16x16x32_bf16 v[28:31], v[176:179], v[192:195], v[28:31]
	v_mfma_f32_16x16x32_bf16 v[24:27], v[184:187], v[192:195], v[24:27]
	v_mfma_f32_16x16x32_bf16 v[20:23], v[176:179], v[218:221], v[20:23]
	v_mfma_f32_16x16x32_bf16 v[16:19], v[184:187], v[218:221], v[16:19]
	v_mfma_f32_16x16x32_bf16 v[12:15], v[176:179], v[226:229], v[12:15]
	v_mfma_f32_16x16x32_bf16 v[8:11], v[184:187], v[226:229], v[8:11]
	v_mfma_f32_16x16x32_bf16 v[4:7], v[176:179], v[234:237], v[4:7]
	v_mfma_f32_16x16x32_bf16 v[0:3], v[184:187], v[234:237], v[0:3]
	s_setprio 0
	s_barrier
	s_add_i32 s37, 0, 0x18000
	v_add_u32_e32 v92, s37, v141
	s_add_i32 s38, 0, 0x1c000
	ds_read_b128 v[152:155], v92
	ds_read_b128 v[160:163], v92 offset:1024
	ds_read_b128 v[164:167], v92 offset:2048
	ds_read_b128 v[168:171], v92 offset:3072
	v_add_u32_e32 v92, s38, v141
	ds_read_b128 v[172:175], v92
	ds_read_b128 v[176:179], v92 offset:1024
	ds_read_b128 v[180:183], v92 offset:2048
	ds_read_b128 v[184:187], v92 offset:3072
	s_add_u32 s10, s10, s16
	s_addc_u32 s11, s11, s17
	s_mov_b32 m0, s56
	v_lshl_add_u64 v[248:249], s[10:11], 0, v[130:131]
	ds_read_b128 v[188:191], v143 offset:32768
	ds_read_b128 v[192:195], v143 offset:33792
	ds_read_b128 v[214:217], v143 offset:34816
	ds_read_b128 v[218:221], v143 offset:35840
	ds_read_b128 v[222:225], v143 offset:36864
	ds_read_b128 v[226:229], v143 offset:37888
	ds_read_b128 v[230:233], v143 offset:38912
	ds_read_b128 v[234:237], v143 offset:39936
	global_load_lds_dwordx4 v[248:249], off
	v_lshl_add_u64 v[248:249], s[10:11], 0, v[134:135]
	s_mov_b32 m0, s57
	s_nop 0
	global_load_lds_dwordx4 v[248:249], off
	s_waitcnt vmcnt(8)
	s_cmp_lg_u32 s26, 0
	s_cbranch_scc1 .Lew_685_11908
	s_waitcnt lgkmcnt(0)
.Lew_685_11908:
	s_barrier
	s_setprio 1
	s_waitcnt lgkmcnt(0)
	v_mfma_f32_16x16x32_bf16 v[126:129], v[152:155], v[188:191], v[126:129]
	v_mfma_f32_16x16x32_bf16 v[122:125], v[164:167], v[188:191], v[122:125]
	v_mfma_f32_16x16x32_bf16 v[118:121], v[152:155], v[214:217], v[118:121]
	v_mfma_f32_16x16x32_bf16 v[114:117], v[164:167], v[214:217], v[114:117]
	v_mfma_f32_16x16x32_bf16 v[110:113], v[152:155], v[222:225], v[110:113]
	v_mfma_f32_16x16x32_bf16 v[106:109], v[164:167], v[222:225], v[106:109]
	v_mfma_f32_16x16x32_bf16 v[102:105], v[152:155], v[230:233], v[102:105]
	v_mfma_f32_16x16x32_bf16 v[98:101], v[164:167], v[230:233], v[98:101]
	v_mfma_f32_16x16x32_bf16 v[126:129], v[160:163], v[192:195], v[126:129]
	v_mfma_f32_16x16x32_bf16 v[122:125], v[168:171], v[192:195], v[122:125]
	v_mfma_f32_16x16x32_bf16 v[118:121], v[160:163], v[218:221], v[118:121]
	v_mfma_f32_16x16x32_bf16 v[114:117], v[168:171], v[218:221], v[114:117]
	v_mfma_f32_16x16x32_bf16 v[110:113], v[160:163], v[226:229], v[110:113]
	v_mfma_f32_16x16x32_bf16 v[106:109], v[168:171], v[226:229], v[106:109]
	v_mfma_f32_16x16x32_bf16 v[102:105], v[160:163], v[234:237], v[102:105]
	v_mfma_f32_16x16x32_bf16 v[98:101], v[168:171], v[234:237], v[98:101]
	s_setprio 0
	s_setprio 1
	v_mfma_f32_16x16x32_bf16 v[60:63], v[172:175], v[188:191], v[60:63]
	v_mfma_f32_16x16x32_bf16 v[56:59], v[180:183], v[188:191], v[56:59]
	v_mfma_f32_16x16x32_bf16 v[52:55], v[172:175], v[214:217], v[52:55]
	v_mfma_f32_16x16x32_bf16 v[48:51], v[180:183], v[214:217], v[48:51]
	v_mfma_f32_16x16x32_bf16 v[44:47], v[172:175], v[222:225], v[44:47]
	v_mfma_f32_16x16x32_bf16 v[40:43], v[180:183], v[222:225], v[40:43]
	v_mfma_f32_16x16x32_bf16 v[36:39], v[172:175], v[230:233], v[36:39]
	v_mfma_f32_16x16x32_bf16 v[32:35], v[180:183], v[230:233], v[32:35]
	v_mfma_f32_16x16x32_bf16 v[60:63], v[176:179], v[192:195], v[60:63]
	v_mfma_f32_16x16x32_bf16 v[56:59], v[184:187], v[192:195], v[56:59]
	v_mfma_f32_16x16x32_bf16 v[52:55], v[176:179], v[218:221], v[52:55]
	v_mfma_f32_16x16x32_bf16 v[48:51], v[184:187], v[218:221], v[48:51]
	v_mfma_f32_16x16x32_bf16 v[44:47], v[176:179], v[226:229], v[44:47]
	v_mfma_f32_16x16x32_bf16 v[40:43], v[184:187], v[226:229], v[40:43]
	v_mfma_f32_16x16x32_bf16 v[36:39], v[176:179], v[234:237], v[36:39]
	v_mfma_f32_16x16x32_bf16 v[32:35], v[184:187], v[234:237], v[32:35]
	s_setprio 0
	s_barrier
	s_add_i32 s10, s37, s53
	v_lshl_add_u64 v[156:157], v[156:157], 0, s[80:81]
	s_mov_b32 m0, s10
	global_load_lds_dwordx4 v[156:157], off
	v_lshl_add_u64 v[156:157], v[238:239], 0, s[80:81]
	s_add_i32 m0, s10, 0x2000
	s_add_i32 s10, s38, s53
	global_load_lds_dwordx4 v[156:157], off
	v_lshl_add_u64 v[156:157], v[240:241], 0, s[80:81]
	s_mov_b32 m0, s10
	s_nop 0
	global_load_lds_dwordx4 v[156:157], off
	v_lshl_add_u64 v[156:157], v[242:243], 0, s[80:81]
	s_add_i32 m0, s10, 0x2000
	s_nop 0
	global_load_lds_dwordx4 v[156:157], off
	v_lshl_add_u64 v[156:157], v[244:245], 0, s[80:81]
	s_mov_b32 m0, s69
	s_nop 0
	global_load_lds_dwordx4 v[156:157], off
	v_lshl_add_u64 v[156:157], v[246:247], 0, s[80:81]
	s_mov_b32 m0, s70
	s_nop 0
	global_load_lds_dwordx4 v[156:157], off
	ds_read_b128 v[188:191], v143 offset:49152
	ds_read_b128 v[192:195], v143 offset:50176
	ds_read_b128 v[214:217], v143 offset:51200
	ds_read_b128 v[218:221], v143 offset:52224
	ds_read_b128 v[222:225], v143 offset:53248
	ds_read_b128 v[226:229], v143 offset:54272
	ds_read_b128 v[230:233], v143 offset:55296
	ds_read_b128 v[234:237], v143 offset:56320
	s_waitcnt vmcnt(8)
	s_cmp_lg_u32 s26, 0
	s_cbranch_scc1 .Lew_685_11986
	s_waitcnt lgkmcnt(0)
.Lew_685_11986:
	s_barrier
	s_setprio 1
	s_waitcnt lgkmcnt(0)
	v_mfma_f32_16x16x32_bf16 v[94:97], v[152:155], v[188:191], v[94:97]
	v_mfma_f32_16x16x32_bf16 v[88:91], v[164:167], v[188:191], v[88:91]
	v_mfma_f32_16x16x32_bf16 v[84:87], v[152:155], v[214:217], v[84:87]
	v_mfma_f32_16x16x32_bf16 v[80:83], v[164:167], v[214:217], v[80:83]
	v_mfma_f32_16x16x32_bf16 v[76:79], v[152:155], v[222:225], v[76:79]
	v_mfma_f32_16x16x32_bf16 v[72:75], v[164:167], v[222:225], v[72:75]
	v_mfma_f32_16x16x32_bf16 v[68:71], v[152:155], v[230:233], v[68:71]
	v_mfma_f32_16x16x32_bf16 v[64:67], v[164:167], v[230:233], v[64:67]
	v_mfma_f32_16x16x32_bf16 v[94:97], v[160:163], v[192:195], v[94:97]
	v_mfma_f32_16x16x32_bf16 v[88:91], v[168:171], v[192:195], v[88:91]
	v_mfma_f32_16x16x32_bf16 v[84:87], v[160:163], v[218:221], v[84:87]
	v_mfma_f32_16x16x32_bf16 v[80:83], v[168:171], v[218:221], v[80:83]
	v_mfma_f32_16x16x32_bf16 v[76:79], v[160:163], v[226:229], v[76:79]
	v_mfma_f32_16x16x32_bf16 v[72:75], v[168:171], v[226:229], v[72:75]
	v_mfma_f32_16x16x32_bf16 v[68:71], v[160:163], v[234:237], v[68:71]
	v_mfma_f32_16x16x32_bf16 v[64:67], v[168:171], v[234:237], v[64:67]
	s_setprio 0
	s_setprio 1
	v_mfma_f32_16x16x32_bf16 v[28:31], v[172:175], v[188:191], v[28:31]
	v_mfma_f32_16x16x32_bf16 v[24:27], v[180:183], v[188:191], v[24:27]
	v_mfma_f32_16x16x32_bf16 v[20:23], v[172:175], v[214:217], v[20:23]
	v_mfma_f32_16x16x32_bf16 v[16:19], v[180:183], v[214:217], v[16:19]
	v_mfma_f32_16x16x32_bf16 v[12:15], v[172:175], v[222:225], v[12:15]
	v_mfma_f32_16x16x32_bf16 v[8:11], v[180:183], v[222:225], v[8:11]
	v_mfma_f32_16x16x32_bf16 v[4:7], v[172:175], v[230:233], v[4:7]
	v_mfma_f32_16x16x32_bf16 v[0:3], v[180:183], v[230:233], v[0:3]
	v_mfma_f32_16x16x32_bf16 v[28:31], v[176:179], v[192:195], v[28:31]
	v_mfma_f32_16x16x32_bf16 v[24:27], v[184:187], v[192:195], v[24:27]
	v_mfma_f32_16x16x32_bf16 v[20:23], v[176:179], v[218:221], v[20:23]
	v_mfma_f32_16x16x32_bf16 v[16:19], v[184:187], v[218:221], v[16:19]
	v_mfma_f32_16x16x32_bf16 v[12:15], v[176:179], v[226:229], v[12:15]
	v_mfma_f32_16x16x32_bf16 v[8:11], v[184:187], v[226:229], v[8:11]
	v_mfma_f32_16x16x32_bf16 v[4:7], v[176:179], v[234:237], v[4:7]
	v_mfma_f32_16x16x32_bf16 v[0:3], v[184:187], v[234:237], v[0:3]
	s_setprio 0
	s_barrier
	s_add_u32 s8, s8, 0x100
	s_addc_u32 s9, s9, 0
	s_add_u32 s34, s34, 0x100
	s_addc_u32 s35, s35, 0
	s_cmp_ge_i32 s36, s68
	s_mov_b32 s10, s36
	s_cbranch_scc0 .LBB0_685

.LBB0_962:
	s_add_i32 s63, s24, 2
	s_add_u32 s64, s26, 0x80
	s_addc_u32 s25, s27, 0
	s_add_i32 s66, 0, 0x10000
	v_add_u32_e32 v79, s66, v77
	ds_read_b128 v[80:83], v79
	ds_read_b128 v[84:87], v79 offset:1024
	ds_read_b128 v[88:91], v79 offset:2048
	ds_read_b128 v[94:97], v79 offset:3072
	s_cmp_eq_u32 s57, s24
	s_cselect_b32 s24, s6, s64
	s_cselect_b32 s25, s7, s25
	s_cselect_b32 s65, s23, s62
	s_cselect_b32 s64, s22, s61
	v_lshl_add_u64 v[130:131], s[26:27], 0, v[72:73]
	s_add_i32 m0, s45, 0xc000
	ds_read_b128 v[98:101], v78
	ds_read_b128 v[102:105], v78 offset:1024
	ds_read_b128 v[106:109], v78 offset:2048
	ds_read_b128 v[110:113], v78 offset:3072
	ds_read_b128 v[114:117], v78 offset:4096
	ds_read_b128 v[118:121], v78 offset:5120
	ds_read_b128 v[122:125], v78 offset:6144
	ds_read_b128 v[126:129], v78 offset:7168
	global_load_lds_dwordx4 v[130:131], off
	v_lshl_add_u64 v[130:131], s[26:27], 0, v[74:75]
	s_add_i32 m0, s45, 0xe000
	s_nop 0
	global_load_lds_dwordx4 v[130:131], off
	s_waitcnt vmcnt(8)
	s_cmp_lg_u32 s20, 0
	s_cbranch_scc1 .Lew_962_15079
	s_waitcnt lgkmcnt(0)
.Lew_962_15079:
	s_barrier
	s_setprio 1
	s_waitcnt lgkmcnt(0)
	v_mfma_f32_16x16x32_bf16 v[60:63], v[80:83], v[98:101], v[60:63]
	v_mfma_f32_16x16x32_bf16 v[56:59], v[88:91], v[98:101], v[56:59]
	v_mfma_f32_16x16x32_bf16 v[52:55], v[80:83], v[106:109], v[52:55]
	v_mfma_f32_16x16x32_bf16 v[48:51], v[88:91], v[106:109], v[48:51]
	v_mfma_f32_16x16x32_bf16 v[44:47], v[80:83], v[114:117], v[44:47]
	v_mfma_f32_16x16x32_bf16 v[40:43], v[88:91], v[114:117], v[40:43]
	v_mfma_f32_16x16x32_bf16 v[36:39], v[80:83], v[122:125], v[36:39]
	v_mfma_f32_16x16x32_bf16 v[32:35], v[88:91], v[122:125], v[32:35]
	v_mfma_f32_16x16x32_bf16 v[60:63], v[84:87], v[102:105], v[60:63]
	v_mfma_f32_16x16x32_bf16 v[56:59], v[94:97], v[102:105], v[56:59]
	v_mfma_f32_16x16x32_bf16 v[52:55], v[84:87], v[110:113], v[52:55]
	v_mfma_f32_16x16x32_bf16 v[48:51], v[94:97], v[110:113], v[48:51]
	v_mfma_f32_16x16x32_bf16 v[44:47], v[84:87], v[118:121], v[44:47]
	v_mfma_f32_16x16x32_bf16 v[40:43], v[94:97], v[118:121], v[40:43]
	v_mfma_f32_16x16x32_bf16 v[36:39], v[84:87], v[126:129], v[36:39]
	v_mfma_f32_16x16x32_bf16 v[32:35], v[94:97], v[126:129], v[32:35]
	s_setprio 0
	s_setprio 1
	s_setprio 0
	s_barrier
	s_add_i32 s66, s66, s40
	v_lshl_add_u64 v[130:131], s[64:65], 0, v[92:93]
	s_mov_b32 m0, s66
	global_load_lds_dwordx4 v[130:131], off
	s_add_i32 m0, s66, 0x2000
	v_lshl_add_u64 v[132:133], s[64:65], 0, v[68:69]
	s_add_u32 s64, s64, s8
	s_addc_u32 s65, s65, s9
	global_load_lds_dwordx4 v[132:133], off
	v_lshl_add_u64 v[134:135], s[64:65], 0, v[92:93]
	s_mov_b32 m0, s46
	v_lshl_add_u64 v[136:137], s[64:65], 0, v[68:69]
	global_load_lds_dwordx4 v[134:135], off
	s_mov_b32 m0, s47
	v_lshl_add_u64 v[138:139], s[24:25], 0, v[64:65]
	global_load_lds_dwordx4 v[136:137], off
	s_mov_b32 m0, s45
	v_lshl_add_u64 v[140:141], s[24:25], 0, v[66:67]
	global_load_lds_dwordx4 v[138:139], off
	s_mov_b32 m0, s48
	s_nop 0
	global_load_lds_dwordx4 v[140:141], off
	ds_read_b128 v[98:101], v78 offset:16384
	ds_read_b128 v[102:105], v78 offset:17408
	ds_read_b128 v[106:109], v78 offset:18432
	ds_read_b128 v[110:113], v78 offset:19456
	ds_read_b128 v[114:117], v78 offset:20480
	ds_read_b128 v[118:121], v78 offset:21504
	ds_read_b128 v[122:125], v78 offset:22528
	ds_read_b128 v[126:129], v78 offset:23552
	s_waitcnt vmcnt(8)
	s_cmp_lg_u32 s20, 0
	s_cbranch_scc1 .Lew_962_15139
	s_waitcnt lgkmcnt(0)
.Lew_962_15139:
	s_barrier
	s_setprio 1
	s_waitcnt lgkmcnt(0)
	v_mfma_f32_16x16x32_bf16 v[28:31], v[80:83], v[98:101], v[28:31]
	v_mfma_f32_16x16x32_bf16 v[24:27], v[88:91], v[98:101], v[24:27]
	v_mfma_f32_16x16x32_bf16 v[20:23], v[80:83], v[106:109], v[20:23]
	v_mfma_f32_16x16x32_bf16 v[16:19], v[88:91], v[106:109], v[16:19]
	v_mfma_f32_16x16x32_bf16 v[12:15], v[80:83], v[114:117], v[12:15]
	v_mfma_f32_16x16x32_bf16 v[8:11], v[88:91], v[114:117], v[8:11]
	v_mfma_f32_16x16x32_bf16 v[4:7], v[80:83], v[122:125], v[4:7]
	v_mfma_f32_16x16x32_bf16 v[0:3], v[88:91], v[122:125], v[0:3]
	v_mfma_f32_16x16x32_bf16 v[28:31], v[84:87], v[102:105], v[28:31]
	v_mfma_f32_16x16x32_bf16 v[24:27], v[94:97], v[102:105], v[24:27]
	v_mfma_f32_16x16x32_bf16 v[20:23], v[84:87], v[110:113], v[20:23]
	v_mfma_f32_16x16x32_bf16 v[16:19], v[94:97], v[110:113], v[16:19]
	v_mfma_f32_16x16x32_bf16 v[12:15], v[84:87], v[118:121], v[12:15]
	v_mfma_f32_16x16x32_bf16 v[8:11], v[94:97], v[118:121], v[8:11]
	v_mfma_f32_16x16x32_bf16 v[4:7], v[84:87], v[126:129], v[4:7]
	v_mfma_f32_16x16x32_bf16 v[0:3], v[94:97], v[126:129], v[0:3]
	s_setprio 0
	s_setprio 1
	s_setprio 0
	s_barrier
	s_add_i32 s64, 0, 0x18000
	v_add_u32_e32 v79, s64, v77
	ds_read_b128 v[80:83], v79
	ds_read_b128 v[84:87], v79 offset:1024
	ds_read_b128 v[88:91], v79 offset:2048
	ds_read_b128 v[94:97], v79 offset:3072
	s_add_u32 s24, s24, s12
	s_addc_u32 s25, s25, s13
	s_mov_b32 m0, s49
	v_lshl_add_u64 v[142:143], s[24:25], 0, v[64:65]
	ds_read_b128 v[98:101], v78 offset:32768
	ds_read_b128 v[102:105], v78 offset:33792
	ds_read_b128 v[106:109], v78 offset:34816
	ds_read_b128 v[110:113], v78 offset:35840
	ds_read_b128 v[114:117], v78 offset:36864
	ds_read_b128 v[118:121], v78 offset:37888
	ds_read_b128 v[122:125], v78 offset:38912
	ds_read_b128 v[126:129], v78 offset:39936
	global_load_lds_dwordx4 v[142:143], off
	v_lshl_add_u64 v[142:143], s[24:25], 0, v[66:67]
	s_mov_b32 m0, s50
	s_nop 0
	global_load_lds_dwordx4 v[142:143], off
	s_waitcnt vmcnt(8)
	s_cmp_lg_u32 s20, 0
	s_cbranch_scc1 .Lew_962_15193
	s_waitcnt lgkmcnt(0)
.Lew_962_15193:
	s_barrier
	s_setprio 1
	s_waitcnt lgkmcnt(0)
	v_mfma_f32_16x16x32_bf16 v[60:63], v[80:83], v[98:101], v[60:63]
	v_mfma_f32_16x16x32_bf16 v[56:59], v[88:91], v[98:101], v[56:59]
	v_mfma_f32_16x16x32_bf16 v[52:55], v[80:83], v[106:109], v[52:55]
	v_mfma_f32_16x16x32_bf16 v[48:51], v[88:91], v[106:109], v[48:51]
	v_mfma_f32_16x16x32_bf16 v[44:47], v[80:83], v[114:117], v[44:47]
	v_mfma_f32_16x16x32_bf16 v[40:43], v[88:91], v[114:117], v[40:43]
	v_mfma_f32_16x16x32_bf16 v[36:39], v[80:83], v[122:125], v[36:39]
	v_mfma_f32_16x16x32_bf16 v[32:35], v[88:91], v[122:125], v[32:35]
	v_mfma_f32_16x16x32_bf16 v[60:63], v[84:87], v[102:105], v[60:63]
	v_mfma_f32_16x16x32_bf16 v[56:59], v[94:97], v[102:105], v[56:59]
	v_mfma_f32_16x16x32_bf16 v[52:55], v[84:87], v[110:113], v[52:55]
	v_mfma_f32_16x16x32_bf16 v[48:51], v[94:97], v[110:113], v[48:51]
	v_mfma_f32_16x16x32_bf16 v[44:47], v[84:87], v[118:121], v[44:47]
	v_mfma_f32_16x16x32_bf16 v[40:43], v[94:97], v[118:121], v[40:43]
	v_mfma_f32_16x16x32_bf16 v[36:39], v[84:87], v[126:129], v[36:39]
	v_mfma_f32_16x16x32_bf16 v[32:35], v[94:97], v[126:129], v[32:35]
	s_setprio 0
	s_setprio 1
	s_setprio 0
	s_barrier
	s_add_i32 s24, s64, s40
	v_lshl_add_u64 v[130:131], v[130:131], 0, s[80:81]
	s_mov_b32 m0, s24
	global_load_lds_dwordx4 v[130:131], off
	v_lshl_add_u64 v[130:131], v[132:133], 0, s[80:81]
	s_add_i32 m0, s24, 0x2000
	s_nop 0
	global_load_lds_dwordx4 v[130:131], off
	v_lshl_add_u64 v[130:131], v[134:135], 0, s[80:81]
	s_mov_b32 m0, s55
	s_nop 0
	global_load_lds_dwordx4 v[130:131], off
	v_lshl_add_u64 v[130:131], v[136:137], 0, s[80:81]
	s_mov_b32 m0, s56
	s_nop 0
	global_load_lds_dwordx4 v[130:131], off
	v_lshl_add_u64 v[130:131], v[138:139], 0, s[80:81]
	s_mov_b32 m0, s53
	s_nop 0
	global_load_lds_dwordx4 v[130:131], off
	v_lshl_add_u64 v[130:131], v[140:141], 0, s[80:81]
	s_mov_b32 m0, s54
	s_nop 0
	global_load_lds_dwordx4 v[130:131], off
	ds_read_b128 v[98:101], v78 offset:49152
	ds_read_b128 v[102:105], v78 offset:50176
	ds_read_b128 v[106:109], v78 offset:51200
	ds_read_b128 v[110:113], v78 offset:52224
	ds_read_b128 v[114:117], v78 offset:53248
	ds_read_b128 v[118:121], v78 offset:54272
	ds_read_b128 v[122:125], v78 offset:55296
	ds_read_b128 v[126:129], v78 offset:56320
	s_waitcnt vmcnt(8)
	s_cmp_lg_u32 s20, 0
	s_cbranch_scc1 .Lew_962_15255
	s_waitcnt lgkmcnt(0)
.Lew_962_15255:
	s_barrier
	s_setprio 1
	s_waitcnt lgkmcnt(0)
	v_mfma_f32_16x16x32_bf16 v[28:31], v[80:83], v[98:101], v[28:31]
	v_mfma_f32_16x16x32_bf16 v[24:27], v[88:91], v[98:101], v[24:27]
	v_mfma_f32_16x16x32_bf16 v[20:23], v[80:83], v[106:109], v[20:23]
	v_mfma_f32_16x16x32_bf16 v[16:19], v[88:91], v[106:109], v[16:19]
	v_mfma_f32_16x16x32_bf16 v[12:15], v[80:83], v[114:117], v[12:15]
	v_mfma_f32_16x16x32_bf16 v[8:11], v[88:91], v[114:117], v[8:11]
	v_mfma_f32_16x16x32_bf16 v[4:7], v[80:83], v[122:125], v[4:7]
	v_mfma_f32_16x16x32_bf16 v[0:3], v[88:91], v[122:125], v[0:3]
	v_mfma_f32_16x16x32_bf16 v[28:31], v[84:87], v[102:105], v[28:31]
	v_mfma_f32_16x16x32_bf16 v[24:27], v[94:97], v[102:105], v[24:27]
	v_mfma_f32_16x16x32_bf16 v[20:23], v[84:87], v[110:113], v[20:23]
	v_mfma_f32_16x16x32_bf16 v[16:19], v[94:97], v[110:113], v[16:19]
	v_mfma_f32_16x16x32_bf16 v[12:15], v[84:87], v[118:121], v[12:15]
	v_mfma_f32_16x16x32_bf16 v[8:11], v[94:97], v[118:121], v[8:11]
	v_mfma_f32_16x16x32_bf16 v[4:7], v[84:87], v[126:129], v[4:7]
	v_mfma_f32_16x16x32_bf16 v[0:3], v[94:97], v[126:129], v[0:3]
	s_setprio 0
	s_setprio 1
	s_setprio 0
	s_barrier
	s_add_u32 s26, s26, 0x100
	s_addc_u32 s27, s27, 0
	s_add_u32 s61, s61, 0x100
	s_addc_u32 s62, s62, 0
	s_cmp_ge_i32 s63, s51
	s_mov_b32 s24, s63
	s_cbranch_scc0 .LBB0_962

.LBB0_1518:
	s_add_i32 s63, s30, 2
	s_add_u32 s64, s28, 0x80
	s_addc_u32 s31, s29, 0
	s_add_i32 s66, 0, 0x10000
	s_cmp_eq_u32 s55, s30
	s_cselect_b32 s31, s7, s31
	s_cselect_b32 s30, s6, s64
	s_cselect_b32 s65, s27, s62
	s_cselect_b32 s64, s26, s61
	s_add_i32 s67, 0, 0x14000
	v_add_u32_e32 v142, s66, v164
	v_add_u32_e32 v156, s67, v164
	ds_read_b128 v[130:133], v142
	ds_read_b128 v[134:137], v142 offset:1024
	ds_read_b128 v[138:141], v142 offset:2048
	ds_read_b128 v[142:145], v142 offset:3072
	ds_read_b128 v[160:163], v156
	ds_read_b128 v[168:171], v156 offset:1024
	ds_read_b128 v[172:175], v156 offset:2048
	ds_read_b128 v[176:179], v156 offset:3072
	v_lshl_add_u64 v[156:157], s[28:29], 0, v[152:153]
	s_add_i32 m0, s46, 0xc000
	ds_read_b128 v[180:183], v166
	ds_read_b128 v[184:187], v166 offset:1024
	ds_read_b128 v[188:191], v166 offset:2048
	ds_read_b128 v[192:195], v166 offset:3072
	ds_read_b128 v[214:217], v166 offset:4096
	ds_read_b128 v[218:221], v166 offset:5120
	ds_read_b128 v[222:225], v166 offset:6144
	ds_read_b128 v[226:229], v166 offset:7168
	global_load_lds_dwordx4 v[156:157], off
	v_lshl_add_u64 v[156:157], s[28:29], 0, v[154:155]
	s_add_i32 m0, s46, 0xe000
	s_nop 0
	global_load_lds_dwordx4 v[156:157], off
	s_waitcnt vmcnt(8)
	s_cmp_lg_u32 s24, 0
	s_cbranch_scc1 .Lew_1518_25158
	s_waitcnt lgkmcnt(0)
.Lew_1518_25158:
	s_barrier
	s_setprio 1
	s_waitcnt lgkmcnt(0)
	v_mfma_f32_16x16x32_bf16 v[126:129], v[130:133], v[180:183], v[126:129]
	v_mfma_f32_16x16x32_bf16 v[122:125], v[138:141], v[180:183], v[122:125]
	v_mfma_f32_16x16x32_bf16 v[110:113], v[130:133], v[188:191], v[110:113]
	v_mfma_f32_16x16x32_bf16 v[106:109], v[138:141], v[188:191], v[106:109]
	v_mfma_f32_16x16x32_bf16 v[94:97], v[130:133], v[214:217], v[94:97]
	v_mfma_f32_16x16x32_bf16 v[88:91], v[138:141], v[214:217], v[88:91]
	v_mfma_f32_16x16x32_bf16 v[76:79], v[130:133], v[222:225], v[76:79]
	v_mfma_f32_16x16x32_bf16 v[72:75], v[138:141], v[222:225], v[72:75]
	v_mfma_f32_16x16x32_bf16 v[126:129], v[134:137], v[184:187], v[126:129]
	v_mfma_f32_16x16x32_bf16 v[122:125], v[142:145], v[184:187], v[122:125]
	v_mfma_f32_16x16x32_bf16 v[110:113], v[134:137], v[192:195], v[110:113]
	v_mfma_f32_16x16x32_bf16 v[106:109], v[142:145], v[192:195], v[106:109]
	v_mfma_f32_16x16x32_bf16 v[94:97], v[134:137], v[218:221], v[94:97]
	v_mfma_f32_16x16x32_bf16 v[88:91], v[142:145], v[218:221], v[88:91]
	v_mfma_f32_16x16x32_bf16 v[76:79], v[134:137], v[226:229], v[76:79]
	v_mfma_f32_16x16x32_bf16 v[72:75], v[142:145], v[226:229], v[72:75]
	s_setprio 0
	s_setprio 1
	v_mfma_f32_16x16x32_bf16 v[118:121], v[160:163], v[180:183], v[118:121]
	v_mfma_f32_16x16x32_bf16 v[114:117], v[172:175], v[180:183], v[114:117]
	v_mfma_f32_16x16x32_bf16 v[102:105], v[160:163], v[188:191], v[102:105]
	v_mfma_f32_16x16x32_bf16 v[98:101], v[172:175], v[188:191], v[98:101]
	v_mfma_f32_16x16x32_bf16 v[84:87], v[160:163], v[214:217], v[84:87]
	v_mfma_f32_16x16x32_bf16 v[80:83], v[172:175], v[214:217], v[80:83]
	v_mfma_f32_16x16x32_bf16 v[68:71], v[160:163], v[222:225], v[68:71]
	v_mfma_f32_16x16x32_bf16 v[64:67], v[172:175], v[222:225], v[64:67]
	v_mfma_f32_16x16x32_bf16 v[118:121], v[168:171], v[184:187], v[118:121]
	v_mfma_f32_16x16x32_bf16 v[114:117], v[176:179], v[184:187], v[114:117]
	v_mfma_f32_16x16x32_bf16 v[102:105], v[168:171], v[192:195], v[102:105]
	v_mfma_f32_16x16x32_bf16 v[98:101], v[176:179], v[192:195], v[98:101]
	v_mfma_f32_16x16x32_bf16 v[84:87], v[168:171], v[218:221], v[84:87]
	v_mfma_f32_16x16x32_bf16 v[80:83], v[176:179], v[218:221], v[80:83]
	v_mfma_f32_16x16x32_bf16 v[68:71], v[168:171], v[226:229], v[68:71]
	v_mfma_f32_16x16x32_bf16 v[64:67], v[176:179], v[226:229], v[64:67]
	s_setprio 0
	s_barrier
	s_add_i32 s66, s66, s41
	v_lshl_add_u64 v[156:157], s[64:65], 0, v[92:93]
	s_mov_b32 m0, s66
	global_load_lds_dwordx4 v[156:157], off
	s_add_i32 m0, s66, 0x2000
	v_lshl_add_u64 v[230:231], s[64:65], 0, v[150:151]
	s_add_u32 s64, s64, s8
	s_addc_u32 s65, s65, s9
	s_add_i32 s66, s67, s41
	global_load_lds_dwordx4 v[230:231], off
	v_lshl_add_u64 v[232:233], s[64:65], 0, v[92:93]
	s_mov_b32 m0, s66
	v_lshl_add_u64 v[234:235], s[64:65], 0, v[150:151]
	global_load_lds_dwordx4 v[232:233], off
	s_add_i32 m0, s66, 0x2000
	v_lshl_add_u64 v[236:237], s[30:31], 0, v[146:147]
	global_load_lds_dwordx4 v[234:235], off
	s_mov_b32 m0, s46
	v_lshl_add_u64 v[238:239], s[30:31], 0, v[148:149]
	global_load_lds_dwordx4 v[236:237], off
	s_mov_b32 m0, s47
	s_nop 0
	global_load_lds_dwordx4 v[238:239], off
	ds_read_b128 v[180:183], v166 offset:16384
	ds_read_b128 v[184:187], v166 offset:17408
	ds_read_b128 v[188:191], v166 offset:18432
	ds_read_b128 v[192:195], v166 offset:19456
	ds_read_b128 v[214:217], v166 offset:20480
	ds_read_b128 v[218:221], v166 offset:21504
	ds_read_b128 v[222:225], v166 offset:22528
	ds_read_b128 v[226:229], v166 offset:23552
	s_waitcnt vmcnt(8)
	s_cmp_lg_u32 s24, 0
	s_cbranch_scc1 .Lew_1518_25235
	s_waitcnt lgkmcnt(0)
.Lew_1518_25235:
	s_barrier
	s_setprio 1
	s_waitcnt lgkmcnt(0)
	v_mfma_f32_16x16x32_bf16 v[60:63], v[130:133], v[180:183], v[60:63]
	v_mfma_f32_16x16x32_bf16 v[56:59], v[138:141], v[180:183], v[56:59]
	v_mfma_f32_16x16x32_bf16 v[44:47], v[130:133], v[188:191], v[44:47]
	v_mfma_f32_16x16x32_bf16 v[40:43], v[138:141], v[188:191], v[40:43]
	v_mfma_f32_16x16x32_bf16 v[28:31], v[130:133], v[214:217], v[28:31]
	v_mfma_f32_16x16x32_bf16 v[24:27], v[138:141], v[214:217], v[24:27]
	v_mfma_f32_16x16x32_bf16 v[12:15], v[130:133], v[222:225], v[12:15]
	v_mfma_f32_16x16x32_bf16 v[8:11], v[138:141], v[222:225], v[8:11]
	v_mfma_f32_16x16x32_bf16 v[60:63], v[134:137], v[184:187], v[60:63]
	v_mfma_f32_16x16x32_bf16 v[56:59], v[142:145], v[184:187], v[56:59]
	v_mfma_f32_16x16x32_bf16 v[44:47], v[134:137], v[192:195], v[44:47]
	v_mfma_f32_16x16x32_bf16 v[40:43], v[142:145], v[192:195], v[40:43]
	v_mfma_f32_16x16x32_bf16 v[28:31], v[134:137], v[218:221], v[28:31]
	v_mfma_f32_16x16x32_bf16 v[24:27], v[142:145], v[218:221], v[24:27]
	v_mfma_f32_16x16x32_bf16 v[12:15], v[134:137], v[226:229], v[12:15]
	v_mfma_f32_16x16x32_bf16 v[8:11], v[142:145], v[226:229], v[8:11]
	s_setprio 0
	s_setprio 1
	v_mfma_f32_16x16x32_bf16 v[52:55], v[160:163], v[180:183], v[52:55]
	v_mfma_f32_16x16x32_bf16 v[48:51], v[172:175], v[180:183], v[48:51]
	v_mfma_f32_16x16x32_bf16 v[36:39], v[160:163], v[188:191], v[36:39]
	v_mfma_f32_16x16x32_bf16 v[32:35], v[172:175], v[188:191], v[32:35]
	v_mfma_f32_16x16x32_bf16 v[20:23], v[160:163], v[214:217], v[20:23]
	v_mfma_f32_16x16x32_bf16 v[16:19], v[172:175], v[214:217], v[16:19]
	v_mfma_f32_16x16x32_bf16 v[4:7], v[160:163], v[222:225], v[4:7]
	v_mfma_f32_16x16x32_bf16 v[0:3], v[172:175], v[222:225], v[0:3]
	v_mfma_f32_16x16x32_bf16 v[52:55], v[168:171], v[184:187], v[52:55]
	v_mfma_f32_16x16x32_bf16 v[48:51], v[176:179], v[184:187], v[48:51]
	v_mfma_f32_16x16x32_bf16 v[36:39], v[168:171], v[192:195], v[36:39]
	v_mfma_f32_16x16x32_bf16 v[32:35], v[176:179], v[192:195], v[32:35]
	v_mfma_f32_16x16x32_bf16 v[20:23], v[168:171], v[218:221], v[20:23]
	v_mfma_f32_16x16x32_bf16 v[16:19], v[176:179], v[218:221], v[16:19]
	v_mfma_f32_16x16x32_bf16 v[4:7], v[168:171], v[226:229], v[4:7]
	v_mfma_f32_16x16x32_bf16 v[0:3], v[176:179], v[226:229], v[0:3]
	s_setprio 0
	s_barrier
	s_add_i32 s64, 0, 0x18000
	s_add_i32 s65, 0, 0x1c000
	v_add_u32_e32 v142, s64, v164
	v_add_u32_e32 v167, s65, v164
	ds_read_b128 v[130:133], v142
	ds_read_b128 v[134:137], v142 offset:1024
	ds_read_b128 v[138:141], v142 offset:2048
	ds_read_b128 v[142:145], v142 offset:3072
	ds_read_b128 v[160:163], v167
	ds_read_b128 v[168:171], v167 offset:1024
	ds_read_b128 v[172:175], v167 offset:2048
	ds_read_b128 v[176:179], v167 offset:3072
	s_add_u32 s30, s30, s12
	s_addc_u32 s31, s31, s13
	s_mov_b32 m0, s48
	v_lshl_add_u64 v[240:241], s[30:31], 0, v[146:147]
	ds_read_b128 v[180:183], v166 offset:32768
	ds_read_b128 v[184:187], v166 offset:33792
	ds_read_b128 v[188:191], v166 offset:34816
	ds_read_b128 v[192:195], v166 offset:35840
	ds_read_b128 v[214:217], v166 offset:36864
	ds_read_b128 v[218:221], v166 offset:37888
	ds_read_b128 v[222:225], v166 offset:38912
	ds_read_b128 v[226:229], v166 offset:39936
	global_load_lds_dwordx4 v[240:241], off
	v_lshl_add_u64 v[240:241], s[30:31], 0, v[148:149]
	s_mov_b32 m0, s49
	s_nop 0
	global_load_lds_dwordx4 v[240:241], off
	s_waitcnt vmcnt(8)
	s_cmp_lg_u32 s24, 0
	s_cbranch_scc1 .Lew_1518_25311
	s_waitcnt lgkmcnt(0)
.Lew_1518_25311:
	s_barrier
	s_setprio 1
	s_waitcnt lgkmcnt(0)
	v_mfma_f32_16x16x32_bf16 v[126:129], v[130:133], v[180:183], v[126:129]
	v_mfma_f32_16x16x32_bf16 v[122:125], v[138:141], v[180:183], v[122:125]
	v_mfma_f32_16x16x32_bf16 v[110:113], v[130:133], v[188:191], v[110:113]
	v_mfma_f32_16x16x32_bf16 v[106:109], v[138:141], v[188:191], v[106:109]
	v_mfma_f32_16x16x32_bf16 v[94:97], v[130:133], v[214:217], v[94:97]
	v_mfma_f32_16x16x32_bf16 v[88:91], v[138:141], v[214:217], v[88:91]
	v_mfma_f32_16x16x32_bf16 v[76:79], v[130:133], v[222:225], v[76:79]
	v_mfma_f32_16x16x32_bf16 v[72:75], v[138:141], v[222:225], v[72:75]
	v_mfma_f32_16x16x32_bf16 v[126:129], v[134:137], v[184:187], v[126:129]
	v_mfma_f32_16x16x32_bf16 v[122:125], v[142:145], v[184:187], v[122:125]
	v_mfma_f32_16x16x32_bf16 v[110:113], v[134:137], v[192:195], v[110:113]
	v_mfma_f32_16x16x32_bf16 v[106:109], v[142:145], v[192:195], v[106:109]
	v_mfma_f32_16x16x32_bf16 v[94:97], v[134:137], v[218:221], v[94:97]
	v_mfma_f32_16x16x32_bf16 v[88:91], v[142:145], v[218:221], v[88:91]
	v_mfma_f32_16x16x32_bf16 v[76:79], v[134:137], v[226:229], v[76:79]
	v_mfma_f32_16x16x32_bf16 v[72:75], v[142:145], v[226:229], v[72:75]
	s_setprio 0
	s_setprio 1
	v_mfma_f32_16x16x32_bf16 v[118:121], v[160:163], v[180:183], v[118:121]
	v_mfma_f32_16x16x32_bf16 v[114:117], v[172:175], v[180:183], v[114:117]
	v_mfma_f32_16x16x32_bf16 v[102:105], v[160:163], v[188:191], v[102:105]
	v_mfma_f32_16x16x32_bf16 v[98:101], v[172:175], v[188:191], v[98:101]
	v_mfma_f32_16x16x32_bf16 v[84:87], v[160:163], v[214:217], v[84:87]
	v_mfma_f32_16x16x32_bf16 v[80:83], v[172:175], v[214:217], v[80:83]
	v_mfma_f32_16x16x32_bf16 v[68:71], v[160:163], v[222:225], v[68:71]
	v_mfma_f32_16x16x32_bf16 v[64:67], v[172:175], v[222:225], v[64:67]
	v_mfma_f32_16x16x32_bf16 v[118:121], v[168:171], v[184:187], v[118:121]
	v_mfma_f32_16x16x32_bf16 v[114:117], v[176:179], v[184:187], v[114:117]
	v_mfma_f32_16x16x32_bf16 v[102:105], v[168:171], v[192:195], v[102:105]
	v_mfma_f32_16x16x32_bf16 v[98:101], v[176:179], v[192:195], v[98:101]
	v_mfma_f32_16x16x32_bf16 v[84:87], v[168:171], v[218:221], v[84:87]
	v_mfma_f32_16x16x32_bf16 v[80:83], v[176:179], v[218:221], v[80:83]
	v_mfma_f32_16x16x32_bf16 v[68:71], v[168:171], v[226:229], v[68:71]
	v_mfma_f32_16x16x32_bf16 v[64:67], v[176:179], v[226:229], v[64:67]
	s_setprio 0
	s_barrier
	s_add_i32 s30, s64, s41
	v_lshl_add_u64 v[156:157], v[156:157], 0, s[80:81]
	s_mov_b32 m0, s30
	global_load_lds_dwordx4 v[156:157], off
	v_lshl_add_u64 v[156:157], v[230:231], 0, s[80:81]
	s_add_i32 m0, s30, 0x2000
	s_add_i32 s30, s65, s41
	global_load_lds_dwordx4 v[156:157], off
	v_lshl_add_u64 v[156:157], v[232:233], 0, s[80:81]
	s_mov_b32 m0, s30
	s_nop 0
	global_load_lds_dwordx4 v[156:157], off
	v_lshl_add_u64 v[156:157], v[234:235], 0, s[80:81]
	s_add_i32 m0, s30, 0x2000
	s_nop 0
	global_load_lds_dwordx4 v[156:157], off
	v_lshl_add_u64 v[156:157], v[236:237], 0, s[80:81]
	s_mov_b32 m0, s53
	s_nop 0
	global_load_lds_dwordx4 v[156:157], off
	v_lshl_add_u64 v[156:157], v[238:239], 0, s[80:81]
	s_mov_b32 m0, s54
	s_nop 0
	global_load_lds_dwordx4 v[156:157], off
	ds_read_b128 v[180:183], v166 offset:49152
	ds_read_b128 v[184:187], v166 offset:50176
	ds_read_b128 v[188:191], v166 offset:51200
	ds_read_b128 v[192:195], v166 offset:52224
	ds_read_b128 v[214:217], v166 offset:53248
	ds_read_b128 v[218:221], v166 offset:54272
	ds_read_b128 v[222:225], v166 offset:55296
	ds_read_b128 v[226:229], v166 offset:56320
	s_waitcnt vmcnt(8)
	s_cmp_lg_u32 s24, 0
	s_cbranch_scc1 .Lew_1518_25389
	s_waitcnt lgkmcnt(0)
.Lew_1518_25389:
	s_barrier
	s_setprio 1
	s_waitcnt lgkmcnt(0)
	v_mfma_f32_16x16x32_bf16 v[60:63], v[130:133], v[180:183], v[60:63]
	v_mfma_f32_16x16x32_bf16 v[56:59], v[138:141], v[180:183], v[56:59]
	v_mfma_f32_16x16x32_bf16 v[44:47], v[130:133], v[188:191], v[44:47]
	v_mfma_f32_16x16x32_bf16 v[40:43], v[138:141], v[188:191], v[40:43]
	v_mfma_f32_16x16x32_bf16 v[28:31], v[130:133], v[214:217], v[28:31]
	v_mfma_f32_16x16x32_bf16 v[24:27], v[138:141], v[214:217], v[24:27]
	v_mfma_f32_16x16x32_bf16 v[12:15], v[130:133], v[222:225], v[12:15]
	v_mfma_f32_16x16x32_bf16 v[8:11], v[138:141], v[222:225], v[8:11]
	v_mfma_f32_16x16x32_bf16 v[60:63], v[134:137], v[184:187], v[60:63]
	v_mfma_f32_16x16x32_bf16 v[56:59], v[142:145], v[184:187], v[56:59]
	v_mfma_f32_16x16x32_bf16 v[44:47], v[134:137], v[192:195], v[44:47]
	v_mfma_f32_16x16x32_bf16 v[40:43], v[142:145], v[192:195], v[40:43]
	v_mfma_f32_16x16x32_bf16 v[28:31], v[134:137], v[218:221], v[28:31]
	v_mfma_f32_16x16x32_bf16 v[24:27], v[142:145], v[218:221], v[24:27]
	v_mfma_f32_16x16x32_bf16 v[12:15], v[134:137], v[226:229], v[12:15]
	v_mfma_f32_16x16x32_bf16 v[8:11], v[142:145], v[226:229], v[8:11]
	s_setprio 0
	s_setprio 1
	v_mfma_f32_16x16x32_bf16 v[52:55], v[160:163], v[180:183], v[52:55]
	v_mfma_f32_16x16x32_bf16 v[48:51], v[172:175], v[180:183], v[48:51]
	v_mfma_f32_16x16x32_bf16 v[36:39], v[160:163], v[188:191], v[36:39]
	v_mfma_f32_16x16x32_bf16 v[32:35], v[172:175], v[188:191], v[32:35]
	v_mfma_f32_16x16x32_bf16 v[20:23], v[160:163], v[214:217], v[20:23]
	v_mfma_f32_16x16x32_bf16 v[16:19], v[172:175], v[214:217], v[16:19]
	v_mfma_f32_16x16x32_bf16 v[4:7], v[160:163], v[222:225], v[4:7]
	v_mfma_f32_16x16x32_bf16 v[0:3], v[172:175], v[222:225], v[0:3]
	v_mfma_f32_16x16x32_bf16 v[52:55], v[168:171], v[184:187], v[52:55]
	v_mfma_f32_16x16x32_bf16 v[48:51], v[176:179], v[184:187], v[48:51]
	v_mfma_f32_16x16x32_bf16 v[36:39], v[168:171], v[192:195], v[36:39]
	v_mfma_f32_16x16x32_bf16 v[32:35], v[176:179], v[192:195], v[32:35]
	v_mfma_f32_16x16x32_bf16 v[20:23], v[168:171], v[218:221], v[20:23]
	v_mfma_f32_16x16x32_bf16 v[16:19], v[176:179], v[218:221], v[16:19]
	v_mfma_f32_16x16x32_bf16 v[4:7], v[168:171], v[226:229], v[4:7]
	v_mfma_f32_16x16x32_bf16 v[0:3], v[176:179], v[226:229], v[0:3]
	s_setprio 0
	s_barrier
	s_add_u32 s28, s28, 0x100
	s_addc_u32 s29, s29, 0
	s_add_u32 s61, s61, 0x100
	s_addc_u32 s62, s62, 0
	s_cmp_ge_i32 s63, s52
	s_mov_b32 s30, s63
	s_cbranch_scc0 .LBB0_1518
	s_movk_i32 s67, 0x4000

.LBB0_1603:
	s_add_i32 s59, s28, 2
	s_add_u32 s60, s26, 0x80
	s_addc_u32 s29, s27, 0
	s_add_i32 s62, 0, 0x10000
	s_cmp_eq_u32 s53, s28
	s_cselect_b32 s29, s7, s29
	s_cselect_b32 s28, s6, s60
	v_add_u32_e32 v156, s62, v141
	s_cselect_b32 s61, s25, s58
	s_cselect_b32 s60, s24, s57
	s_add_i32 s63, 0, 0x14000
	ds_read_b128 v[144:147], v156
	ds_read_b128 v[148:151], v156 offset:1024
	ds_read_b128 v[152:155], v156 offset:2048
	ds_read_b128 v[160:163], v156 offset:3072
	v_add_u32_e32 v156, s63, v141
	ds_read_b128 v[164:167], v156
	ds_read_b128 v[168:171], v156 offset:1024
	ds_read_b128 v[172:175], v156 offset:2048
	ds_read_b128 v[176:179], v156 offset:3072
	v_lshl_add_u64 v[156:157], s[26:27], 0, v[136:137]
	s_add_i32 m0, s44, 0xc000
	ds_read_b128 v[180:183], v143
	ds_read_b128 v[184:187], v143 offset:1024
	ds_read_b128 v[188:191], v143 offset:2048
	ds_read_b128 v[192:195], v143 offset:3072
	ds_read_b128 v[214:217], v143 offset:4096
	ds_read_b128 v[218:221], v143 offset:5120
	ds_read_b128 v[222:225], v143 offset:6144
	ds_read_b128 v[226:229], v143 offset:7168
	global_load_lds_dwordx4 v[156:157], off
	v_lshl_add_u64 v[156:157], s[26:27], 0, v[138:139]
	s_add_i32 m0, s44, 0xe000
	s_nop 0
	global_load_lds_dwordx4 v[156:157], off
	s_waitcnt vmcnt(8)
	s_cmp_lg_u32 s22, 0
	s_cbranch_scc1 .Lew_1603_26610
	s_waitcnt lgkmcnt(0)
.Lew_1603_26610:
	s_barrier
	s_setprio 1
	s_waitcnt lgkmcnt(0)
	v_mfma_f32_16x16x32_bf16 v[122:125], v[144:147], v[180:183], v[122:125]
	v_mfma_f32_16x16x32_bf16 v[126:129], v[152:155], v[180:183], v[126:129]
	v_mfma_f32_16x16x32_bf16 v[110:113], v[144:147], v[188:191], v[110:113]
	v_mfma_f32_16x16x32_bf16 v[106:109], v[152:155], v[188:191], v[106:109]
	v_mfma_f32_16x16x32_bf16 v[94:97], v[144:147], v[214:217], v[94:97]
	v_mfma_f32_16x16x32_bf16 v[88:91], v[152:155], v[214:217], v[88:91]
	v_mfma_f32_16x16x32_bf16 v[76:79], v[144:147], v[222:225], v[76:79]
	v_mfma_f32_16x16x32_bf16 v[72:75], v[152:155], v[222:225], v[72:75]
	v_mfma_f32_16x16x32_bf16 v[122:125], v[148:151], v[184:187], v[122:125]
	v_mfma_f32_16x16x32_bf16 v[126:129], v[160:163], v[184:187], v[126:129]
	v_mfma_f32_16x16x32_bf16 v[110:113], v[148:151], v[192:195], v[110:113]
	v_mfma_f32_16x16x32_bf16 v[106:109], v[160:163], v[192:195], v[106:109]
	v_mfma_f32_16x16x32_bf16 v[94:97], v[148:151], v[218:221], v[94:97]
	v_mfma_f32_16x16x32_bf16 v[88:91], v[160:163], v[218:221], v[88:91]
	v_mfma_f32_16x16x32_bf16 v[76:79], v[148:151], v[226:229], v[76:79]
	v_mfma_f32_16x16x32_bf16 v[72:75], v[160:163], v[226:229], v[72:75]
	s_setprio 0
	s_setprio 1
	v_mfma_f32_16x16x32_bf16 v[118:121], v[164:167], v[180:183], v[118:121]
	v_mfma_f32_16x16x32_bf16 v[114:117], v[172:175], v[180:183], v[114:117]
	v_mfma_f32_16x16x32_bf16 v[102:105], v[164:167], v[188:191], v[102:105]
	v_mfma_f32_16x16x32_bf16 v[98:101], v[172:175], v[188:191], v[98:101]
	v_mfma_f32_16x16x32_bf16 v[84:87], v[164:167], v[214:217], v[84:87]
	v_mfma_f32_16x16x32_bf16 v[80:83], v[172:175], v[214:217], v[80:83]
	v_mfma_f32_16x16x32_bf16 v[68:71], v[164:167], v[222:225], v[68:71]
	v_mfma_f32_16x16x32_bf16 v[64:67], v[172:175], v[222:225], v[64:67]
	v_mfma_f32_16x16x32_bf16 v[118:121], v[168:171], v[184:187], v[118:121]
	v_mfma_f32_16x16x32_bf16 v[114:117], v[176:179], v[184:187], v[114:117]
	v_mfma_f32_16x16x32_bf16 v[102:105], v[168:171], v[192:195], v[102:105]
	v_mfma_f32_16x16x32_bf16 v[98:101], v[176:179], v[192:195], v[98:101]
	v_mfma_f32_16x16x32_bf16 v[84:87], v[168:171], v[218:221], v[84:87]
	v_mfma_f32_16x16x32_bf16 v[80:83], v[176:179], v[218:221], v[80:83]
	v_mfma_f32_16x16x32_bf16 v[68:71], v[168:171], v[226:229], v[68:71]
	v_mfma_f32_16x16x32_bf16 v[64:67], v[176:179], v[226:229], v[64:67]
	s_setprio 0
	s_barrier
	s_add_i32 s62, s62, s39
	v_lshl_add_u64 v[156:157], s[60:61], 0, v[92:93]
	s_mov_b32 m0, s62
	global_load_lds_dwordx4 v[156:157], off
	s_add_i32 m0, s62, 0x2000
	v_lshl_add_u64 v[230:231], s[60:61], 0, v[134:135]
	s_add_u32 s60, s60, s8
	s_addc_u32 s61, s61, s9
	s_add_i32 s62, s63, s39
	global_load_lds_dwordx4 v[230:231], off
	v_lshl_add_u64 v[232:233], s[60:61], 0, v[92:93]
	s_mov_b32 m0, s62
	v_lshl_add_u64 v[234:235], s[60:61], 0, v[134:135]
	global_load_lds_dwordx4 v[232:233], off
	s_add_i32 m0, s62, 0x2000
	v_lshl_add_u64 v[236:237], s[28:29], 0, v[130:131]
	global_load_lds_dwordx4 v[234:235], off
	s_mov_b32 m0, s44
	v_lshl_add_u64 v[238:239], s[28:29], 0, v[132:133]
	global_load_lds_dwordx4 v[236:237], off
	s_mov_b32 m0, s45
	s_nop 0
	global_load_lds_dwordx4 v[238:239], off
	ds_read_b128 v[180:183], v143 offset:16384
	ds_read_b128 v[184:187], v143 offset:17408
	ds_read_b128 v[188:191], v143 offset:18432
	ds_read_b128 v[192:195], v143 offset:19456
	ds_read_b128 v[214:217], v143 offset:20480
	ds_read_b128 v[218:221], v143 offset:21504
	ds_read_b128 v[222:225], v143 offset:22528
	ds_read_b128 v[226:229], v143 offset:23552
	s_waitcnt vmcnt(8)
	s_cmp_lg_u32 s22, 0
	s_cbranch_scc1 .Lew_1603_26687
	s_waitcnt lgkmcnt(0)
.Lew_1603_26687:
	s_barrier
	s_setprio 1
	s_waitcnt lgkmcnt(0)
	v_mfma_f32_16x16x32_bf16 v[60:63], v[144:147], v[180:183], v[60:63]
	v_mfma_f32_16x16x32_bf16 v[56:59], v[152:155], v[180:183], v[56:59]
	v_mfma_f32_16x16x32_bf16 v[44:47], v[144:147], v[188:191], v[44:47]
	v_mfma_f32_16x16x32_bf16 v[40:43], v[152:155], v[188:191], v[40:43]
	v_mfma_f32_16x16x32_bf16 v[28:31], v[144:147], v[214:217], v[28:31]
	v_mfma_f32_16x16x32_bf16 v[24:27], v[152:155], v[214:217], v[24:27]
	v_mfma_f32_16x16x32_bf16 v[12:15], v[144:147], v[222:225], v[12:15]
	v_mfma_f32_16x16x32_bf16 v[8:11], v[152:155], v[222:225], v[8:11]
	v_mfma_f32_16x16x32_bf16 v[60:63], v[148:151], v[184:187], v[60:63]
	v_mfma_f32_16x16x32_bf16 v[56:59], v[160:163], v[184:187], v[56:59]
	v_mfma_f32_16x16x32_bf16 v[44:47], v[148:151], v[192:195], v[44:47]
	v_mfma_f32_16x16x32_bf16 v[40:43], v[160:163], v[192:195], v[40:43]
	v_mfma_f32_16x16x32_bf16 v[28:31], v[148:151], v[218:221], v[28:31]
	v_mfma_f32_16x16x32_bf16 v[24:27], v[160:163], v[218:221], v[24:27]
	v_mfma_f32_16x16x32_bf16 v[12:15], v[148:151], v[226:229], v[12:15]
	v_mfma_f32_16x16x32_bf16 v[8:11], v[160:163], v[226:229], v[8:11]
	s_setprio 0
	s_setprio 1
	v_mfma_f32_16x16x32_bf16 v[52:55], v[164:167], v[180:183], v[52:55]
	v_mfma_f32_16x16x32_bf16 v[48:51], v[172:175], v[180:183], v[48:51]
	v_mfma_f32_16x16x32_bf16 v[36:39], v[164:167], v[188:191], v[36:39]
	v_mfma_f32_16x16x32_bf16 v[32:35], v[172:175], v[188:191], v[32:35]
	v_mfma_f32_16x16x32_bf16 v[20:23], v[164:167], v[214:217], v[20:23]
	v_mfma_f32_16x16x32_bf16 v[16:19], v[172:175], v[214:217], v[16:19]
	v_mfma_f32_16x16x32_bf16 v[4:7], v[164:167], v[222:225], v[4:7]
	v_mfma_f32_16x16x32_bf16 v[0:3], v[172:175], v[222:225], v[0:3]
	v_mfma_f32_16x16x32_bf16 v[52:55], v[168:171], v[184:187], v[52:55]
	v_mfma_f32_16x16x32_bf16 v[48:51], v[176:179], v[184:187], v[48:51]
	v_mfma_f32_16x16x32_bf16 v[36:39], v[168:171], v[192:195], v[36:39]
	v_mfma_f32_16x16x32_bf16 v[32:35], v[176:179], v[192:195], v[32:35]
	v_mfma_f32_16x16x32_bf16 v[20:23], v[168:171], v[218:221], v[20:23]
	v_mfma_f32_16x16x32_bf16 v[16:19], v[176:179], v[218:221], v[16:19]
	v_mfma_f32_16x16x32_bf16 v[4:7], v[168:171], v[226:229], v[4:7]
	v_mfma_f32_16x16x32_bf16 v[0:3], v[176:179], v[226:229], v[0:3]
	s_setprio 0
	s_barrier
	s_add_i32 s60, 0, 0x18000
	v_add_u32_e32 v159, s60, v141
	s_add_i32 s61, 0, 0x1c000
	ds_read_b128 v[144:147], v159
	ds_read_b128 v[148:151], v159 offset:1024
	ds_read_b128 v[152:155], v159 offset:2048
	ds_read_b128 v[160:163], v159 offset:3072
	v_add_u32_e32 v159, s61, v141
	ds_read_b128 v[164:167], v159
	ds_read_b128 v[168:171], v159 offset:1024
	ds_read_b128 v[172:175], v159 offset:2048
	ds_read_b128 v[176:179], v159 offset:3072
	s_add_u32 s28, s28, s12
	s_addc_u32 s29, s29, s13
	s_mov_b32 m0, s46
	v_lshl_add_u64 v[240:241], s[28:29], 0, v[130:131]
	ds_read_b128 v[180:183], v143 offset:32768
	ds_read_b128 v[184:187], v143 offset:33792
	ds_read_b128 v[188:191], v143 offset:34816
	ds_read_b128 v[192:195], v143 offset:35840
	ds_read_b128 v[214:217], v143 offset:36864
	ds_read_b128 v[218:221], v143 offset:37888
	ds_read_b128 v[222:225], v143 offset:38912
	ds_read_b128 v[226:229], v143 offset:39936
	global_load_lds_dwordx4 v[240:241], off
	v_lshl_add_u64 v[240:241], s[28:29], 0, v[132:133]
	s_mov_b32 m0, s47
	s_nop 0
	global_load_lds_dwordx4 v[240:241], off
	s_waitcnt vmcnt(8)
	s_cmp_lg_u32 s22, 0
	s_cbranch_scc1 .Lew_1603_26763
	s_waitcnt lgkmcnt(0)
.Lew_1603_26763:
	s_barrier
	s_setprio 1
	s_waitcnt lgkmcnt(0)
	v_mfma_f32_16x16x32_bf16 v[122:125], v[144:147], v[180:183], v[122:125]
	v_mfma_f32_16x16x32_bf16 v[126:129], v[152:155], v[180:183], v[126:129]
	v_mfma_f32_16x16x32_bf16 v[110:113], v[144:147], v[188:191], v[110:113]
	v_mfma_f32_16x16x32_bf16 v[106:109], v[152:155], v[188:191], v[106:109]
	v_mfma_f32_16x16x32_bf16 v[94:97], v[144:147], v[214:217], v[94:97]
	v_mfma_f32_16x16x32_bf16 v[88:91], v[152:155], v[214:217], v[88:91]
	v_mfma_f32_16x16x32_bf16 v[76:79], v[144:147], v[222:225], v[76:79]
	v_mfma_f32_16x16x32_bf16 v[72:75], v[152:155], v[222:225], v[72:75]
	v_mfma_f32_16x16x32_bf16 v[122:125], v[148:151], v[184:187], v[122:125]
	v_mfma_f32_16x16x32_bf16 v[126:129], v[160:163], v[184:187], v[126:129]
	v_mfma_f32_16x16x32_bf16 v[110:113], v[148:151], v[192:195], v[110:113]
	v_mfma_f32_16x16x32_bf16 v[106:109], v[160:163], v[192:195], v[106:109]
	v_mfma_f32_16x16x32_bf16 v[94:97], v[148:151], v[218:221], v[94:97]
	v_mfma_f32_16x16x32_bf16 v[88:91], v[160:163], v[218:221], v[88:91]
	v_mfma_f32_16x16x32_bf16 v[76:79], v[148:151], v[226:229], v[76:79]
	v_mfma_f32_16x16x32_bf16 v[72:75], v[160:163], v[226:229], v[72:75]
	s_setprio 0
	s_setprio 1
	v_mfma_f32_16x16x32_bf16 v[118:121], v[164:167], v[180:183], v[118:121]
	v_mfma_f32_16x16x32_bf16 v[114:117], v[172:175], v[180:183], v[114:117]
	v_mfma_f32_16x16x32_bf16 v[102:105], v[164:167], v[188:191], v[102:105]
	v_mfma_f32_16x16x32_bf16 v[98:101], v[172:175], v[188:191], v[98:101]
	v_mfma_f32_16x16x32_bf16 v[84:87], v[164:167], v[214:217], v[84:87]
	v_mfma_f32_16x16x32_bf16 v[80:83], v[172:175], v[214:217], v[80:83]
	v_mfma_f32_16x16x32_bf16 v[68:71], v[164:167], v[222:225], v[68:71]
	v_mfma_f32_16x16x32_bf16 v[64:67], v[172:175], v[222:225], v[64:67]
	v_mfma_f32_16x16x32_bf16 v[118:121], v[168:171], v[184:187], v[118:121]
	v_mfma_f32_16x16x32_bf16 v[114:117], v[176:179], v[184:187], v[114:117]
	v_mfma_f32_16x16x32_bf16 v[102:105], v[168:171], v[192:195], v[102:105]
	v_mfma_f32_16x16x32_bf16 v[98:101], v[176:179], v[192:195], v[98:101]
	v_mfma_f32_16x16x32_bf16 v[84:87], v[168:171], v[218:221], v[84:87]
	v_mfma_f32_16x16x32_bf16 v[80:83], v[176:179], v[218:221], v[80:83]
	v_mfma_f32_16x16x32_bf16 v[68:71], v[168:171], v[226:229], v[68:71]
	v_mfma_f32_16x16x32_bf16 v[64:67], v[176:179], v[226:229], v[64:67]
	s_setprio 0
	s_barrier
	s_add_i32 s28, s60, s39
	v_lshl_add_u64 v[156:157], v[156:157], 0, s[80:81]
	s_mov_b32 m0, s28
	global_load_lds_dwordx4 v[156:157], off
	v_lshl_add_u64 v[156:157], v[230:231], 0, s[80:81]
	s_add_i32 m0, s28, 0x2000
	s_add_i32 s28, s61, s39
	global_load_lds_dwordx4 v[156:157], off
	v_lshl_add_u64 v[156:157], v[232:233], 0, s[80:81]
	s_mov_b32 m0, s28
	s_nop 0
	global_load_lds_dwordx4 v[156:157], off
	v_lshl_add_u64 v[156:157], v[234:235], 0, s[80:81]
	s_add_i32 m0, s28, 0x2000
	s_nop 0
	global_load_lds_dwordx4 v[156:157], off
	v_lshl_add_u64 v[156:157], v[236:237], 0, s[80:81]
	s_mov_b32 m0, s51
	s_nop 0
	global_load_lds_dwordx4 v[156:157], off
	v_lshl_add_u64 v[156:157], v[238:239], 0, s[80:81]
	s_mov_b32 m0, s52
	s_nop 0
	global_load_lds_dwordx4 v[156:157], off
	ds_read_b128 v[180:183], v143 offset:49152
	ds_read_b128 v[184:187], v143 offset:50176
	ds_read_b128 v[188:191], v143 offset:51200
	ds_read_b128 v[192:195], v143 offset:52224
	ds_read_b128 v[214:217], v143 offset:53248
	ds_read_b128 v[218:221], v143 offset:54272
	ds_read_b128 v[222:225], v143 offset:55296
	ds_read_b128 v[226:229], v143 offset:56320
	s_waitcnt vmcnt(8)
	s_cmp_lg_u32 s22, 0
	s_cbranch_scc1 .Lew_1603_26841
	s_waitcnt lgkmcnt(0)
.Lew_1603_26841:
	s_barrier
	s_setprio 1
	s_waitcnt lgkmcnt(0)
	v_mfma_f32_16x16x32_bf16 v[60:63], v[144:147], v[180:183], v[60:63]
	v_mfma_f32_16x16x32_bf16 v[56:59], v[152:155], v[180:183], v[56:59]
	v_mfma_f32_16x16x32_bf16 v[44:47], v[144:147], v[188:191], v[44:47]
	v_mfma_f32_16x16x32_bf16 v[40:43], v[152:155], v[188:191], v[40:43]
	v_mfma_f32_16x16x32_bf16 v[28:31], v[144:147], v[214:217], v[28:31]
	v_mfma_f32_16x16x32_bf16 v[24:27], v[152:155], v[214:217], v[24:27]
	v_mfma_f32_16x16x32_bf16 v[12:15], v[144:147], v[222:225], v[12:15]
	v_mfma_f32_16x16x32_bf16 v[8:11], v[152:155], v[222:225], v[8:11]
	v_mfma_f32_16x16x32_bf16 v[60:63], v[148:151], v[184:187], v[60:63]
	v_mfma_f32_16x16x32_bf16 v[56:59], v[160:163], v[184:187], v[56:59]
	v_mfma_f32_16x16x32_bf16 v[44:47], v[148:151], v[192:195], v[44:47]
	v_mfma_f32_16x16x32_bf16 v[40:43], v[160:163], v[192:195], v[40:43]
	v_mfma_f32_16x16x32_bf16 v[28:31], v[148:151], v[218:221], v[28:31]
	v_mfma_f32_16x16x32_bf16 v[24:27], v[160:163], v[218:221], v[24:27]
	v_mfma_f32_16x16x32_bf16 v[12:15], v[148:151], v[226:229], v[12:15]
	v_mfma_f32_16x16x32_bf16 v[8:11], v[160:163], v[226:229], v[8:11]
	s_setprio 0
	s_setprio 1
	v_mfma_f32_16x16x32_bf16 v[52:55], v[164:167], v[180:183], v[52:55]
	v_mfma_f32_16x16x32_bf16 v[48:51], v[172:175], v[180:183], v[48:51]
	v_mfma_f32_16x16x32_bf16 v[36:39], v[164:167], v[188:191], v[36:39]
	v_mfma_f32_16x16x32_bf16 v[32:35], v[172:175], v[188:191], v[32:35]
	v_mfma_f32_16x16x32_bf16 v[20:23], v[164:167], v[214:217], v[20:23]
	v_mfma_f32_16x16x32_bf16 v[16:19], v[172:175], v[214:217], v[16:19]
	v_mfma_f32_16x16x32_bf16 v[4:7], v[164:167], v[222:225], v[4:7]
	v_mfma_f32_16x16x32_bf16 v[0:3], v[172:175], v[222:225], v[0:3]
	v_mfma_f32_16x16x32_bf16 v[52:55], v[168:171], v[184:187], v[52:55]
	v_mfma_f32_16x16x32_bf16 v[48:51], v[176:179], v[184:187], v[48:51]
	v_mfma_f32_16x16x32_bf16 v[36:39], v[168:171], v[192:195], v[36:39]
	v_mfma_f32_16x16x32_bf16 v[32:35], v[176:179], v[192:195], v[32:35]
	v_mfma_f32_16x16x32_bf16 v[20:23], v[168:171], v[218:221], v[20:23]
	v_mfma_f32_16x16x32_bf16 v[16:19], v[176:179], v[218:221], v[16:19]
	v_mfma_f32_16x16x32_bf16 v[4:7], v[168:171], v[226:229], v[4:7]
	v_mfma_f32_16x16x32_bf16 v[0:3], v[176:179], v[226:229], v[0:3]
	s_setprio 0
	s_barrier
	s_add_u32 s26, s26, 0x100
	s_addc_u32 s27, s27, 0
	s_add_u32 s57, s57, 0x100
	s_addc_u32 s58, s58, 0
	s_cmp_ge_i32 s59, s48
	s_mov_b32 s28, s59
	s_cbranch_scc0 .LBB0_1603

.LBB0_1749:
	s_add_i32 s59, s28, 2
	s_add_u32 s60, s6, 0x80
	s_addc_u32 s29, s7, 0
	s_add_i32 s62, 0, 0x10000
	s_cmp_eq_u32 s46, s28
	s_cselect_b32 s29, s25, s29
	s_cselect_b32 s28, s24, s60
	v_add_u32_e32 v157, s62, v155
	s_cselect_b32 s61, s27, s31
	s_cselect_b32 s60, s26, s30
	s_add_i32 s63, 0, 0x14000
	ds_read_b128 v[146:149], v157
	ds_read_b128 v[150:153], v157 offset:1024
	ds_read_b128 v[160:163], v157 offset:2048
	ds_read_b128 v[164:167], v157 offset:3072
	v_add_u32_e32 v157, s63, v155
	ds_read_b128 v[168:171], v157
	ds_read_b128 v[172:175], v157 offset:1024
	ds_read_b128 v[176:179], v157 offset:2048
	ds_read_b128 v[180:183], v157 offset:3072
	v_lshl_add_u64 v[234:235], s[6:7], 0, v[142:143]
	s_add_i32 m0, s38, 0xc000
	ds_read_b128 v[184:187], v156
	ds_read_b128 v[188:191], v156 offset:1024
	ds_read_b128 v[192:195], v156 offset:2048
	ds_read_b128 v[214:217], v156 offset:3072
	ds_read_b128 v[218:221], v156 offset:4096
	ds_read_b128 v[222:225], v156 offset:5120
	ds_read_b128 v[226:229], v156 offset:6144
	ds_read_b128 v[230:233], v156 offset:7168
	global_load_lds_dwordx4 v[234:235], off
	v_lshl_add_u64 v[234:235], s[6:7], 0, v[144:145]
	s_add_i32 m0, s38, 0xe000
	s_nop 0
	global_load_lds_dwordx4 v[234:235], off
	s_waitcnt vmcnt(8)
	s_cmp_lg_u32 s22, 0
	s_cbranch_scc1 .Lew_1749_28695
	s_waitcnt lgkmcnt(0)
.Lew_1749_28695:
	s_barrier
	s_setprio 1
	s_waitcnt lgkmcnt(0)
	v_mfma_f32_16x16x32_bf16 v[126:129], v[146:149], v[184:187], v[126:129]
	v_mfma_f32_16x16x32_bf16 v[122:125], v[160:163], v[184:187], v[122:125]
	v_mfma_f32_16x16x32_bf16 v[118:121], v[146:149], v[192:195], v[118:121]
	v_mfma_f32_16x16x32_bf16 v[114:117], v[160:163], v[192:195], v[114:117]
	v_mfma_f32_16x16x32_bf16 v[110:113], v[146:149], v[218:221], v[110:113]
	v_mfma_f32_16x16x32_bf16 v[106:109], v[160:163], v[218:221], v[106:109]
	v_mfma_f32_16x16x32_bf16 v[102:105], v[146:149], v[226:229], v[102:105]
	v_mfma_f32_16x16x32_bf16 v[98:101], v[160:163], v[226:229], v[98:101]
	v_mfma_f32_16x16x32_bf16 v[126:129], v[150:153], v[188:191], v[126:129]
	v_mfma_f32_16x16x32_bf16 v[122:125], v[164:167], v[188:191], v[122:125]
	v_mfma_f32_16x16x32_bf16 v[118:121], v[150:153], v[214:217], v[118:121]
	v_mfma_f32_16x16x32_bf16 v[114:117], v[164:167], v[214:217], v[114:117]
	v_mfma_f32_16x16x32_bf16 v[110:113], v[150:153], v[222:225], v[110:113]
	v_mfma_f32_16x16x32_bf16 v[106:109], v[164:167], v[222:225], v[106:109]
	v_mfma_f32_16x16x32_bf16 v[102:105], v[150:153], v[230:233], v[102:105]
	v_mfma_f32_16x16x32_bf16 v[98:101], v[164:167], v[230:233], v[98:101]
	s_setprio 0
	s_setprio 1
	v_mfma_f32_16x16x32_bf16 v[60:63], v[168:171], v[184:187], v[60:63]
	v_mfma_f32_16x16x32_bf16 v[56:59], v[176:179], v[184:187], v[56:59]
	v_mfma_f32_16x16x32_bf16 v[52:55], v[168:171], v[192:195], v[52:55]
	v_mfma_f32_16x16x32_bf16 v[48:51], v[176:179], v[192:195], v[48:51]
	v_mfma_f32_16x16x32_bf16 v[44:47], v[168:171], v[218:221], v[44:47]
	v_mfma_f32_16x16x32_bf16 v[40:43], v[176:179], v[218:221], v[40:43]
	v_mfma_f32_16x16x32_bf16 v[36:39], v[168:171], v[226:229], v[36:39]
	v_mfma_f32_16x16x32_bf16 v[32:35], v[176:179], v[226:229], v[32:35]
	v_mfma_f32_16x16x32_bf16 v[60:63], v[172:175], v[188:191], v[60:63]
	v_mfma_f32_16x16x32_bf16 v[56:59], v[180:183], v[188:191], v[56:59]
	v_mfma_f32_16x16x32_bf16 v[52:55], v[172:175], v[214:217], v[52:55]
	v_mfma_f32_16x16x32_bf16 v[48:51], v[180:183], v[214:217], v[48:51]
	v_mfma_f32_16x16x32_bf16 v[44:47], v[172:175], v[222:225], v[44:47]
	v_mfma_f32_16x16x32_bf16 v[40:43], v[180:183], v[222:225], v[40:43]
	v_mfma_f32_16x16x32_bf16 v[36:39], v[172:175], v[230:233], v[36:39]
	v_mfma_f32_16x16x32_bf16 v[32:35], v[180:183], v[230:233], v[32:35]
	s_setprio 0
	s_barrier
	s_add_i32 s62, s62, s37
	v_lshl_add_u64 v[234:235], s[60:61], 0, v[92:93]
	s_mov_b32 m0, s62
	global_load_lds_dwordx4 v[234:235], off
	s_add_i32 m0, s62, 0x2000
	v_lshl_add_u64 v[236:237], s[60:61], 0, v[134:135]
	s_add_u32 s60, s60, s8
	s_addc_u32 s61, s61, s9
	s_add_i32 s62, s63, s37
	global_load_lds_dwordx4 v[236:237], off
	v_lshl_add_u64 v[238:239], s[60:61], 0, v[92:93]
	s_mov_b32 m0, s62
	v_lshl_add_u64 v[240:241], s[60:61], 0, v[134:135]
	global_load_lds_dwordx4 v[238:239], off
	s_add_i32 m0, s62, 0x2000
	v_lshl_add_u64 v[242:243], s[28:29], 0, v[130:131]
	global_load_lds_dwordx4 v[240:241], off
	s_mov_b32 m0, s38
	v_lshl_add_u64 v[244:245], s[28:29], 0, v[132:133]
	global_load_lds_dwordx4 v[242:243], off
	s_mov_b32 m0, s39
	s_nop 0
	global_load_lds_dwordx4 v[244:245], off
	ds_read_b128 v[184:187], v156 offset:16384
	ds_read_b128 v[188:191], v156 offset:17408
	ds_read_b128 v[192:195], v156 offset:18432
	ds_read_b128 v[214:217], v156 offset:19456
	ds_read_b128 v[218:221], v156 offset:20480
	ds_read_b128 v[222:225], v156 offset:21504
	ds_read_b128 v[226:229], v156 offset:22528
	ds_read_b128 v[230:233], v156 offset:23552
	s_waitcnt vmcnt(8)
	s_cmp_lg_u32 s22, 0
	s_cbranch_scc1 .Lew_1749_28772
	s_waitcnt lgkmcnt(0)
.Lew_1749_28772:
	s_barrier
	s_setprio 1
	s_waitcnt lgkmcnt(0)
	v_mfma_f32_16x16x32_bf16 v[94:97], v[146:149], v[184:187], v[94:97]
	v_mfma_f32_16x16x32_bf16 v[88:91], v[160:163], v[184:187], v[88:91]
	v_mfma_f32_16x16x32_bf16 v[84:87], v[146:149], v[192:195], v[84:87]
	v_mfma_f32_16x16x32_bf16 v[80:83], v[160:163], v[192:195], v[80:83]
	v_mfma_f32_16x16x32_bf16 v[76:79], v[146:149], v[218:221], v[76:79]
	v_mfma_f32_16x16x32_bf16 v[72:75], v[160:163], v[218:221], v[72:75]
	v_mfma_f32_16x16x32_bf16 v[68:71], v[146:149], v[226:229], v[68:71]
	v_mfma_f32_16x16x32_bf16 v[64:67], v[160:163], v[226:229], v[64:67]
	v_mfma_f32_16x16x32_bf16 v[94:97], v[150:153], v[188:191], v[94:97]
	v_mfma_f32_16x16x32_bf16 v[88:91], v[164:167], v[188:191], v[88:91]
	v_mfma_f32_16x16x32_bf16 v[84:87], v[150:153], v[214:217], v[84:87]
	v_mfma_f32_16x16x32_bf16 v[80:83], v[164:167], v[214:217], v[80:83]
	v_mfma_f32_16x16x32_bf16 v[76:79], v[150:153], v[222:225], v[76:79]
	v_mfma_f32_16x16x32_bf16 v[72:75], v[164:167], v[222:225], v[72:75]
	v_mfma_f32_16x16x32_bf16 v[68:71], v[150:153], v[230:233], v[68:71]
	v_mfma_f32_16x16x32_bf16 v[64:67], v[164:167], v[230:233], v[64:67]
	s_setprio 0
	s_setprio 1
	v_mfma_f32_16x16x32_bf16 v[28:31], v[168:171], v[184:187], v[28:31]
	v_mfma_f32_16x16x32_bf16 v[24:27], v[176:179], v[184:187], v[24:27]
	v_mfma_f32_16x16x32_bf16 v[20:23], v[168:171], v[192:195], v[20:23]
	v_mfma_f32_16x16x32_bf16 v[16:19], v[176:179], v[192:195], v[16:19]
	v_mfma_f32_16x16x32_bf16 v[12:15], v[168:171], v[218:221], v[12:15]
	v_mfma_f32_16x16x32_bf16 v[8:11], v[176:179], v[218:221], v[8:11]
	v_mfma_f32_16x16x32_bf16 v[4:7], v[168:171], v[226:229], v[4:7]
	v_mfma_f32_16x16x32_bf16 v[0:3], v[176:179], v[226:229], v[0:3]
	v_mfma_f32_16x16x32_bf16 v[28:31], v[172:175], v[188:191], v[28:31]
	v_mfma_f32_16x16x32_bf16 v[24:27], v[180:183], v[188:191], v[24:27]
	v_mfma_f32_16x16x32_bf16 v[20:23], v[172:175], v[214:217], v[20:23]
	v_mfma_f32_16x16x32_bf16 v[16:19], v[180:183], v[214:217], v[16:19]
	v_mfma_f32_16x16x32_bf16 v[12:15], v[172:175], v[222:225], v[12:15]
	v_mfma_f32_16x16x32_bf16 v[8:11], v[180:183], v[222:225], v[8:11]
	v_mfma_f32_16x16x32_bf16 v[4:7], v[172:175], v[230:233], v[4:7]
	v_mfma_f32_16x16x32_bf16 v[0:3], v[180:183], v[230:233], v[0:3]
	s_setprio 0
	s_barrier
	s_add_i32 s60, 0, 0x18000
	v_add_u32_e32 v157, s60, v155
	s_add_i32 s61, 0, 0x1c000
	ds_read_b128 v[146:149], v157
	ds_read_b128 v[150:153], v157 offset:1024
	ds_read_b128 v[160:163], v157 offset:2048
	ds_read_b128 v[164:167], v157 offset:3072
	v_add_u32_e32 v157, s61, v155
	ds_read_b128 v[168:171], v157
	ds_read_b128 v[172:175], v157 offset:1024
	ds_read_b128 v[176:179], v157 offset:2048
	ds_read_b128 v[180:183], v157 offset:3072
	s_add_u32 s28, s28, s12
	s_addc_u32 s29, s29, s13
	s_mov_b32 m0, s40
	v_lshl_add_u64 v[246:247], s[28:29], 0, v[130:131]
	ds_read_b128 v[184:187], v156 offset:32768
	ds_read_b128 v[188:191], v156 offset:33792
	ds_read_b128 v[192:195], v156 offset:34816
	ds_read_b128 v[214:217], v156 offset:35840
	ds_read_b128 v[218:221], v156 offset:36864
	ds_read_b128 v[222:225], v156 offset:37888
	ds_read_b128 v[226:229], v156 offset:38912
	ds_read_b128 v[230:233], v156 offset:39936
	global_load_lds_dwordx4 v[246:247], off
	v_lshl_add_u64 v[246:247], s[28:29], 0, v[132:133]
	s_mov_b32 m0, s41
	s_nop 0
	global_load_lds_dwordx4 v[246:247], off
	s_waitcnt vmcnt(8)
	s_cmp_lg_u32 s22, 0
	s_cbranch_scc1 .Lew_1749_28848
	s_waitcnt lgkmcnt(0)
.Lew_1749_28848:
	s_barrier
	s_setprio 1
	s_waitcnt lgkmcnt(0)
	v_mfma_f32_16x16x32_bf16 v[126:129], v[146:149], v[184:187], v[126:129]
	v_mfma_f32_16x16x32_bf16 v[122:125], v[160:163], v[184:187], v[122:125]
	v_mfma_f32_16x16x32_bf16 v[118:121], v[146:149], v[192:195], v[118:121]
	v_mfma_f32_16x16x32_bf16 v[114:117], v[160:163], v[192:195], v[114:117]
	v_mfma_f32_16x16x32_bf16 v[110:113], v[146:149], v[218:221], v[110:113]
	v_mfma_f32_16x16x32_bf16 v[106:109], v[160:163], v[218:221], v[106:109]
	v_mfma_f32_16x16x32_bf16 v[102:105], v[146:149], v[226:229], v[102:105]
	v_mfma_f32_16x16x32_bf16 v[98:101], v[160:163], v[226:229], v[98:101]
	v_mfma_f32_16x16x32_bf16 v[126:129], v[150:153], v[188:191], v[126:129]
	v_mfma_f32_16x16x32_bf16 v[122:125], v[164:167], v[188:191], v[122:125]
	v_mfma_f32_16x16x32_bf16 v[118:121], v[150:153], v[214:217], v[118:121]
	v_mfma_f32_16x16x32_bf16 v[114:117], v[164:167], v[214:217], v[114:117]
	v_mfma_f32_16x16x32_bf16 v[110:113], v[150:153], v[222:225], v[110:113]
	v_mfma_f32_16x16x32_bf16 v[106:109], v[164:167], v[222:225], v[106:109]
	v_mfma_f32_16x16x32_bf16 v[102:105], v[150:153], v[230:233], v[102:105]
	v_mfma_f32_16x16x32_bf16 v[98:101], v[164:167], v[230:233], v[98:101]
	s_setprio 0
	s_setprio 1
	v_mfma_f32_16x16x32_bf16 v[60:63], v[168:171], v[184:187], v[60:63]
	v_mfma_f32_16x16x32_bf16 v[56:59], v[176:179], v[184:187], v[56:59]
	v_mfma_f32_16x16x32_bf16 v[52:55], v[168:171], v[192:195], v[52:55]
	v_mfma_f32_16x16x32_bf16 v[48:51], v[176:179], v[192:195], v[48:51]
	v_mfma_f32_16x16x32_bf16 v[44:47], v[168:171], v[218:221], v[44:47]
	v_mfma_f32_16x16x32_bf16 v[40:43], v[176:179], v[218:221], v[40:43]
	v_mfma_f32_16x16x32_bf16 v[36:39], v[168:171], v[226:229], v[36:39]
	v_mfma_f32_16x16x32_bf16 v[32:35], v[176:179], v[226:229], v[32:35]
	v_mfma_f32_16x16x32_bf16 v[60:63], v[172:175], v[188:191], v[60:63]
	v_mfma_f32_16x16x32_bf16 v[56:59], v[180:183], v[188:191], v[56:59]
	v_mfma_f32_16x16x32_bf16 v[52:55], v[172:175], v[214:217], v[52:55]
	v_mfma_f32_16x16x32_bf16 v[48:51], v[180:183], v[214:217], v[48:51]
	v_mfma_f32_16x16x32_bf16 v[44:47], v[172:175], v[222:225], v[44:47]
	v_mfma_f32_16x16x32_bf16 v[40:43], v[180:183], v[222:225], v[40:43]
	v_mfma_f32_16x16x32_bf16 v[36:39], v[172:175], v[230:233], v[36:39]
	v_mfma_f32_16x16x32_bf16 v[32:35], v[180:183], v[230:233], v[32:35]
	s_setprio 0
	s_barrier
	s_add_i32 s28, s60, s37
	v_lshl_add_u64 v[234:235], v[234:235], 0, s[80:81]
	s_mov_b32 m0, s28
	global_load_lds_dwordx4 v[234:235], off
	v_lshl_add_u64 v[234:235], v[236:237], 0, s[80:81]
	s_add_i32 m0, s28, 0x2000
	s_add_i32 s28, s61, s37
	global_load_lds_dwordx4 v[234:235], off
	v_lshl_add_u64 v[234:235], v[238:239], 0, s[80:81]
	s_mov_b32 m0, s28
	s_nop 0
	global_load_lds_dwordx4 v[234:235], off
	v_lshl_add_u64 v[234:235], v[240:241], 0, s[80:81]
	s_add_i32 m0, s28, 0x2000
	s_nop 0
	global_load_lds_dwordx4 v[234:235], off
	v_lshl_add_u64 v[234:235], v[242:243], 0, s[80:81]
	s_mov_b32 m0, s42
	s_nop 0
	global_load_lds_dwordx4 v[234:235], off
	v_lshl_add_u64 v[234:235], v[244:245], 0, s[80:81]
	s_mov_b32 m0, s43
	s_nop 0
	global_load_lds_dwordx4 v[234:235], off
	ds_read_b128 v[184:187], v156 offset:49152
	ds_read_b128 v[188:191], v156 offset:50176
	ds_read_b128 v[192:195], v156 offset:51200
	ds_read_b128 v[214:217], v156 offset:52224
	ds_read_b128 v[218:221], v156 offset:53248
	ds_read_b128 v[222:225], v156 offset:54272
	ds_read_b128 v[226:229], v156 offset:55296
	ds_read_b128 v[230:233], v156 offset:56320
	s_waitcnt vmcnt(8)
	s_cmp_lg_u32 s22, 0
	s_cbranch_scc1 .Lew_1749_28926
	s_waitcnt lgkmcnt(0)
.Lew_1749_28926:
	s_barrier
	s_setprio 1
	s_waitcnt lgkmcnt(0)
	v_mfma_f32_16x16x32_bf16 v[94:97], v[146:149], v[184:187], v[94:97]
	v_mfma_f32_16x16x32_bf16 v[88:91], v[160:163], v[184:187], v[88:91]
	v_mfma_f32_16x16x32_bf16 v[84:87], v[146:149], v[192:195], v[84:87]
	v_mfma_f32_16x16x32_bf16 v[80:83], v[160:163], v[192:195], v[80:83]
	v_mfma_f32_16x16x32_bf16 v[76:79], v[146:149], v[218:221], v[76:79]
	v_mfma_f32_16x16x32_bf16 v[72:75], v[160:163], v[218:221], v[72:75]
	v_mfma_f32_16x16x32_bf16 v[68:71], v[146:149], v[226:229], v[68:71]
	v_mfma_f32_16x16x32_bf16 v[64:67], v[160:163], v[226:229], v[64:67]
	v_mfma_f32_16x16x32_bf16 v[94:97], v[150:153], v[188:191], v[94:97]
	v_mfma_f32_16x16x32_bf16 v[88:91], v[164:167], v[188:191], v[88:91]
	v_mfma_f32_16x16x32_bf16 v[84:87], v[150:153], v[214:217], v[84:87]
	v_mfma_f32_16x16x32_bf16 v[80:83], v[164:167], v[214:217], v[80:83]
	v_mfma_f32_16x16x32_bf16 v[76:79], v[150:153], v[222:225], v[76:79]
	v_mfma_f32_16x16x32_bf16 v[72:75], v[164:167], v[222:225], v[72:75]
	v_mfma_f32_16x16x32_bf16 v[68:71], v[150:153], v[230:233], v[68:71]
	v_mfma_f32_16x16x32_bf16 v[64:67], v[164:167], v[230:233], v[64:67]
	s_setprio 0
	s_setprio 1
	v_mfma_f32_16x16x32_bf16 v[28:31], v[168:171], v[184:187], v[28:31]
	v_mfma_f32_16x16x32_bf16 v[24:27], v[176:179], v[184:187], v[24:27]
	v_mfma_f32_16x16x32_bf16 v[20:23], v[168:171], v[192:195], v[20:23]
	v_mfma_f32_16x16x32_bf16 v[16:19], v[176:179], v[192:195], v[16:19]
	v_mfma_f32_16x16x32_bf16 v[12:15], v[168:171], v[218:221], v[12:15]
	v_mfma_f32_16x16x32_bf16 v[8:11], v[176:179], v[218:221], v[8:11]
	v_mfma_f32_16x16x32_bf16 v[4:7], v[168:171], v[226:229], v[4:7]
	v_mfma_f32_16x16x32_bf16 v[0:3], v[176:179], v[226:229], v[0:3]
	v_mfma_f32_16x16x32_bf16 v[28:31], v[172:175], v[188:191], v[28:31]
	v_mfma_f32_16x16x32_bf16 v[24:27], v[180:183], v[188:191], v[24:27]
	v_mfma_f32_16x16x32_bf16 v[20:23], v[172:175], v[214:217], v[20:23]
	v_mfma_f32_16x16x32_bf16 v[16:19], v[180:183], v[214:217], v[16:19]
	v_mfma_f32_16x16x32_bf16 v[12:15], v[172:175], v[222:225], v[12:15]
	v_mfma_f32_16x16x32_bf16 v[8:11], v[180:183], v[222:225], v[8:11]
	v_mfma_f32_16x16x32_bf16 v[4:7], v[172:175], v[230:233], v[4:7]
	v_mfma_f32_16x16x32_bf16 v[0:3], v[180:183], v[230:233], v[0:3]
	s_setprio 0
	s_barrier
	s_add_u32 s6, s6, 0x100
	s_addc_u32 s7, s7, 0
	s_add_u32 s30, s30, 0x100
	s_addc_u32 s31, s31, 0
	s_cmp_ge_i32 s59, s44
	s_mov_b32 s28, s59
	s_cbranch_scc0 .LBB0_1749

.LBB0_1812:
	s_add_i32 s60, s30, 2
	s_add_u32 s61, s6, 0x80
	s_addc_u32 s31, s7, 0
	s_add_i32 s64, 0, 0x10000
	s_cmp_eq_u32 s47, s30
	s_cselect_b32 s31, s27, s31
	s_cselect_b32 s30, s26, s61
	v_add_u32_e32 v92, s64, v150
	s_cselect_b32 s63, s29, s35
	s_cselect_b32 s62, s28, s34
	s_add_i32 s61, 0, 0x14000
	ds_read_b128 v[146:149], v92
	ds_read_b128 v[152:155], v92 offset:1024
	ds_read_b128 v[160:163], v92 offset:2048
	ds_read_b128 v[164:167], v92 offset:3072
	v_add_u32_e32 v92, s61, v150
	ds_read_b128 v[168:171], v92
	ds_read_b128 v[172:175], v92 offset:1024
	ds_read_b128 v[176:179], v92 offset:2048
	ds_read_b128 v[180:183], v92 offset:3072
	v_lshl_add_u64 v[156:157], s[6:7], 0, v[142:143]
	s_add_i32 m0, s40, 0xc000
	ds_read_b128 v[184:187], v151
	ds_read_b128 v[188:191], v151 offset:1024
	ds_read_b128 v[192:195], v151 offset:2048
	ds_read_b128 v[214:217], v151 offset:3072
	ds_read_b128 v[218:221], v151 offset:4096
	ds_read_b128 v[222:225], v151 offset:5120
	ds_read_b128 v[226:229], v151 offset:6144
	ds_read_b128 v[230:233], v151 offset:7168
	global_load_lds_dwordx4 v[156:157], off
	v_lshl_add_u64 v[156:157], s[6:7], 0, v[144:145]
	s_add_i32 m0, s40, 0xe000
	s_nop 0
	global_load_lds_dwordx4 v[156:157], off
	s_waitcnt vmcnt(8)
	s_cmp_lg_u32 s22, 0
	s_cbranch_scc1 .Lew_1812_30766
	s_waitcnt lgkmcnt(0)
.Lew_1812_30766:
	s_barrier
	s_setprio 1
	s_waitcnt lgkmcnt(0)
	v_mfma_f32_16x16x32_bf16 v[126:129], v[146:149], v[184:187], v[126:129]
	v_mfma_f32_16x16x32_bf16 v[122:125], v[160:163], v[184:187], v[122:125]
	v_mfma_f32_16x16x32_bf16 v[118:121], v[146:149], v[192:195], v[118:121]
	v_mfma_f32_16x16x32_bf16 v[114:117], v[160:163], v[192:195], v[114:117]
	v_mfma_f32_16x16x32_bf16 v[110:113], v[146:149], v[218:221], v[110:113]
	v_mfma_f32_16x16x32_bf16 v[106:109], v[160:163], v[218:221], v[106:109]
	v_mfma_f32_16x16x32_bf16 v[102:105], v[146:149], v[226:229], v[102:105]
	v_mfma_f32_16x16x32_bf16 v[98:101], v[160:163], v[226:229], v[98:101]
	v_mfma_f32_16x16x32_bf16 v[126:129], v[152:155], v[188:191], v[126:129]
	v_mfma_f32_16x16x32_bf16 v[122:125], v[164:167], v[188:191], v[122:125]
	v_mfma_f32_16x16x32_bf16 v[118:121], v[152:155], v[214:217], v[118:121]
	v_mfma_f32_16x16x32_bf16 v[114:117], v[164:167], v[214:217], v[114:117]
	v_mfma_f32_16x16x32_bf16 v[110:113], v[152:155], v[222:225], v[110:113]
	v_mfma_f32_16x16x32_bf16 v[106:109], v[164:167], v[222:225], v[106:109]
	v_mfma_f32_16x16x32_bf16 v[102:105], v[152:155], v[230:233], v[102:105]
	v_mfma_f32_16x16x32_bf16 v[98:101], v[164:167], v[230:233], v[98:101]
	s_setprio 0
	s_setprio 1
	v_mfma_f32_16x16x32_bf16 v[60:63], v[168:171], v[184:187], v[60:63]
	v_mfma_f32_16x16x32_bf16 v[56:59], v[176:179], v[184:187], v[56:59]
	v_mfma_f32_16x16x32_bf16 v[52:55], v[168:171], v[192:195], v[52:55]
	v_mfma_f32_16x16x32_bf16 v[48:51], v[176:179], v[192:195], v[48:51]
	v_mfma_f32_16x16x32_bf16 v[44:47], v[168:171], v[218:221], v[44:47]
	v_mfma_f32_16x16x32_bf16 v[40:43], v[176:179], v[218:221], v[40:43]
	v_mfma_f32_16x16x32_bf16 v[36:39], v[168:171], v[226:229], v[36:39]
	v_mfma_f32_16x16x32_bf16 v[32:35], v[176:179], v[226:229], v[32:35]
	v_mfma_f32_16x16x32_bf16 v[60:63], v[172:175], v[188:191], v[60:63]
	v_mfma_f32_16x16x32_bf16 v[56:59], v[180:183], v[188:191], v[56:59]
	v_mfma_f32_16x16x32_bf16 v[52:55], v[172:175], v[214:217], v[52:55]
	v_mfma_f32_16x16x32_bf16 v[48:51], v[180:183], v[214:217], v[48:51]
	v_mfma_f32_16x16x32_bf16 v[44:47], v[172:175], v[222:225], v[44:47]
	v_mfma_f32_16x16x32_bf16 v[40:43], v[180:183], v[222:225], v[40:43]
	v_mfma_f32_16x16x32_bf16 v[36:39], v[172:175], v[230:233], v[36:39]
	v_mfma_f32_16x16x32_bf16 v[32:35], v[180:183], v[230:233], v[32:35]
	s_setprio 0
	s_barrier
	s_add_i32 s64, s64, s39
	v_lshl_add_u64 v[156:157], s[62:63], 0, v[132:133]
	s_mov_b32 m0, s64
	global_load_lds_dwordx4 v[156:157], off
	s_add_i32 m0, s64, 0x2000
	v_lshl_add_u64 v[234:235], s[62:63], 0, v[136:137]
	s_add_u32 s62, s62, s8
	s_addc_u32 s63, s63, s9
	s_add_i32 s61, s61, s39
	global_load_lds_dwordx4 v[234:235], off
	v_lshl_add_u64 v[236:237], s[62:63], 0, v[132:133]
	s_mov_b32 m0, s61
	v_lshl_add_u64 v[238:239], s[62:63], 0, v[136:137]
	global_load_lds_dwordx4 v[236:237], off
	s_add_i32 m0, s61, 0x2000
	v_lshl_add_u64 v[240:241], s[30:31], 0, v[130:131]
	global_load_lds_dwordx4 v[238:239], off
	s_mov_b32 m0, s40
	v_lshl_add_u64 v[242:243], s[30:31], 0, v[134:135]
	global_load_lds_dwordx4 v[240:241], off
	s_mov_b32 m0, s41
	s_nop 0
	global_load_lds_dwordx4 v[242:243], off
	ds_read_b128 v[184:187], v151 offset:16384
	ds_read_b128 v[188:191], v151 offset:17408
	ds_read_b128 v[192:195], v151 offset:18432
	ds_read_b128 v[214:217], v151 offset:19456
	ds_read_b128 v[218:221], v151 offset:20480
	ds_read_b128 v[222:225], v151 offset:21504
	ds_read_b128 v[226:229], v151 offset:22528
	ds_read_b128 v[230:233], v151 offset:23552
	s_waitcnt vmcnt(8)
	s_cmp_lg_u32 s22, 0
	s_cbranch_scc1 .Lew_1812_30843
	s_waitcnt lgkmcnt(0)
.Lew_1812_30843:
	s_barrier
	s_setprio 1
	s_waitcnt lgkmcnt(0)
	v_mfma_f32_16x16x32_bf16 v[94:97], v[146:149], v[184:187], v[94:97]
	v_mfma_f32_16x16x32_bf16 v[88:91], v[160:163], v[184:187], v[88:91]
	v_mfma_f32_16x16x32_bf16 v[84:87], v[146:149], v[192:195], v[84:87]
	v_mfma_f32_16x16x32_bf16 v[80:83], v[160:163], v[192:195], v[80:83]
	v_mfma_f32_16x16x32_bf16 v[76:79], v[146:149], v[218:221], v[76:79]
	v_mfma_f32_16x16x32_bf16 v[72:75], v[160:163], v[218:221], v[72:75]
	v_mfma_f32_16x16x32_bf16 v[68:71], v[146:149], v[226:229], v[68:71]
	v_mfma_f32_16x16x32_bf16 v[64:67], v[160:163], v[226:229], v[64:67]
	v_mfma_f32_16x16x32_bf16 v[94:97], v[152:155], v[188:191], v[94:97]
	v_mfma_f32_16x16x32_bf16 v[88:91], v[164:167], v[188:191], v[88:91]
	v_mfma_f32_16x16x32_bf16 v[84:87], v[152:155], v[214:217], v[84:87]
	v_mfma_f32_16x16x32_bf16 v[80:83], v[164:167], v[214:217], v[80:83]
	v_mfma_f32_16x16x32_bf16 v[76:79], v[152:155], v[222:225], v[76:79]
	v_mfma_f32_16x16x32_bf16 v[72:75], v[164:167], v[222:225], v[72:75]
	v_mfma_f32_16x16x32_bf16 v[68:71], v[152:155], v[230:233], v[68:71]
	v_mfma_f32_16x16x32_bf16 v[64:67], v[164:167], v[230:233], v[64:67]
	s_setprio 0
	s_setprio 1
	v_mfma_f32_16x16x32_bf16 v[28:31], v[168:171], v[184:187], v[28:31]
	v_mfma_f32_16x16x32_bf16 v[24:27], v[176:179], v[184:187], v[24:27]
	v_mfma_f32_16x16x32_bf16 v[20:23], v[168:171], v[192:195], v[20:23]
	v_mfma_f32_16x16x32_bf16 v[16:19], v[176:179], v[192:195], v[16:19]
	v_mfma_f32_16x16x32_bf16 v[12:15], v[168:171], v[218:221], v[12:15]
	v_mfma_f32_16x16x32_bf16 v[8:11], v[176:179], v[218:221], v[8:11]
	v_mfma_f32_16x16x32_bf16 v[4:7], v[168:171], v[226:229], v[4:7]
	v_mfma_f32_16x16x32_bf16 v[0:3], v[176:179], v[226:229], v[0:3]
	v_mfma_f32_16x16x32_bf16 v[28:31], v[172:175], v[188:191], v[28:31]
	v_mfma_f32_16x16x32_bf16 v[24:27], v[180:183], v[188:191], v[24:27]
	v_mfma_f32_16x16x32_bf16 v[20:23], v[172:175], v[214:217], v[20:23]
	v_mfma_f32_16x16x32_bf16 v[16:19], v[180:183], v[214:217], v[16:19]
	v_mfma_f32_16x16x32_bf16 v[12:15], v[172:175], v[222:225], v[12:15]
	v_mfma_f32_16x16x32_bf16 v[8:11], v[180:183], v[222:225], v[8:11]
	v_mfma_f32_16x16x32_bf16 v[4:7], v[172:175], v[230:233], v[4:7]
	v_mfma_f32_16x16x32_bf16 v[0:3], v[180:183], v[230:233], v[0:3]
	s_setprio 0
	s_barrier
	s_add_i32 s61, 0, 0x18000
	v_add_u32_e32 v92, s61, v150
	s_add_i32 s62, 0, 0x1c000
	ds_read_b128 v[146:149], v92
	ds_read_b128 v[152:155], v92 offset:1024
	ds_read_b128 v[160:163], v92 offset:2048
	ds_read_b128 v[164:167], v92 offset:3072
	v_add_u32_e32 v92, s62, v150
	ds_read_b128 v[168:171], v92
	ds_read_b128 v[172:175], v92 offset:1024
	ds_read_b128 v[176:179], v92 offset:2048
	ds_read_b128 v[180:183], v92 offset:3072
	s_add_u32 s30, s30, s12
	s_addc_u32 s31, s31, s13
	s_mov_b32 m0, s42
	v_lshl_add_u64 v[244:245], s[30:31], 0, v[130:131]
	ds_read_b128 v[184:187], v151 offset:32768
	ds_read_b128 v[188:191], v151 offset:33792
	ds_read_b128 v[192:195], v151 offset:34816
	ds_read_b128 v[214:217], v151 offset:35840
	ds_read_b128 v[218:221], v151 offset:36864
	ds_read_b128 v[222:225], v151 offset:37888
	ds_read_b128 v[226:229], v151 offset:38912
	ds_read_b128 v[230:233], v151 offset:39936
	global_load_lds_dwordx4 v[244:245], off
	v_lshl_add_u64 v[244:245], s[30:31], 0, v[134:135]
	s_mov_b32 m0, s43
	s_nop 0
	global_load_lds_dwordx4 v[244:245], off
	s_waitcnt vmcnt(8)
	s_cmp_lg_u32 s22, 0
	s_cbranch_scc1 .Lew_1812_30919
	s_waitcnt lgkmcnt(0)
.Lew_1812_30919:
	s_barrier
	s_setprio 1
	s_waitcnt lgkmcnt(0)
	v_mfma_f32_16x16x32_bf16 v[126:129], v[146:149], v[184:187], v[126:129]
	v_mfma_f32_16x16x32_bf16 v[122:125], v[160:163], v[184:187], v[122:125]
	v_mfma_f32_16x16x32_bf16 v[118:121], v[146:149], v[192:195], v[118:121]
	v_mfma_f32_16x16x32_bf16 v[114:117], v[160:163], v[192:195], v[114:117]
	v_mfma_f32_16x16x32_bf16 v[110:113], v[146:149], v[218:221], v[110:113]
	v_mfma_f32_16x16x32_bf16 v[106:109], v[160:163], v[218:221], v[106:109]
	v_mfma_f32_16x16x32_bf16 v[102:105], v[146:149], v[226:229], v[102:105]
	v_mfma_f32_16x16x32_bf16 v[98:101], v[160:163], v[226:229], v[98:101]
	v_mfma_f32_16x16x32_bf16 v[126:129], v[152:155], v[188:191], v[126:129]
	v_mfma_f32_16x16x32_bf16 v[122:125], v[164:167], v[188:191], v[122:125]
	v_mfma_f32_16x16x32_bf16 v[118:121], v[152:155], v[214:217], v[118:121]
	v_mfma_f32_16x16x32_bf16 v[114:117], v[164:167], v[214:217], v[114:117]
	v_mfma_f32_16x16x32_bf16 v[110:113], v[152:155], v[222:225], v[110:113]
	v_mfma_f32_16x16x32_bf16 v[106:109], v[164:167], v[222:225], v[106:109]
	v_mfma_f32_16x16x32_bf16 v[102:105], v[152:155], v[230:233], v[102:105]
	v_mfma_f32_16x16x32_bf16 v[98:101], v[164:167], v[230:233], v[98:101]
	s_setprio 0
	s_setprio 1
	v_mfma_f32_16x16x32_bf16 v[60:63], v[168:171], v[184:187], v[60:63]
	v_mfma_f32_16x16x32_bf16 v[56:59], v[176:179], v[184:187], v[56:59]
	v_mfma_f32_16x16x32_bf16 v[52:55], v[168:171], v[192:195], v[52:55]
	v_mfma_f32_16x16x32_bf16 v[48:51], v[176:179], v[192:195], v[48:51]
	v_mfma_f32_16x16x32_bf16 v[44:47], v[168:171], v[218:221], v[44:47]
	v_mfma_f32_16x16x32_bf16 v[40:43], v[176:179], v[218:221], v[40:43]
	v_mfma_f32_16x16x32_bf16 v[36:39], v[168:171], v[226:229], v[36:39]
	v_mfma_f32_16x16x32_bf16 v[32:35], v[176:179], v[226:229], v[32:35]
	v_mfma_f32_16x16x32_bf16 v[60:63], v[172:175], v[188:191], v[60:63]
	v_mfma_f32_16x16x32_bf16 v[56:59], v[180:183], v[188:191], v[56:59]
	v_mfma_f32_16x16x32_bf16 v[52:55], v[172:175], v[214:217], v[52:55]
	v_mfma_f32_16x16x32_bf16 v[48:51], v[180:183], v[214:217], v[48:51]
	v_mfma_f32_16x16x32_bf16 v[44:47], v[172:175], v[222:225], v[44:47]
	v_mfma_f32_16x16x32_bf16 v[40:43], v[180:183], v[222:225], v[40:43]
	v_mfma_f32_16x16x32_bf16 v[36:39], v[172:175], v[230:233], v[36:39]
	v_mfma_f32_16x16x32_bf16 v[32:35], v[180:183], v[230:233], v[32:35]
	s_setprio 0
	s_barrier
	s_add_i32 s30, s61, s39
	v_lshl_add_u64 v[156:157], v[156:157], 0, s[80:81]
	s_mov_b32 m0, s30
	global_load_lds_dwordx4 v[156:157], off
	v_lshl_add_u64 v[156:157], v[234:235], 0, s[80:81]
	s_add_i32 m0, s30, 0x2000
	s_add_i32 s30, s62, s39
	global_load_lds_dwordx4 v[156:157], off
	v_lshl_add_u64 v[156:157], v[236:237], 0, s[80:81]
	s_mov_b32 m0, s30
	s_nop 0
	global_load_lds_dwordx4 v[156:157], off
	v_lshl_add_u64 v[156:157], v[238:239], 0, s[80:81]
	s_add_i32 m0, s30, 0x2000
	s_nop 0
	global_load_lds_dwordx4 v[156:157], off
	v_lshl_add_u64 v[156:157], v[240:241], 0, s[80:81]
	s_mov_b32 m0, s45
	s_nop 0
	global_load_lds_dwordx4 v[156:157], off
	v_lshl_add_u64 v[156:157], v[242:243], 0, s[80:81]
	s_mov_b32 m0, s46
	s_nop 0
	global_load_lds_dwordx4 v[156:157], off
	ds_read_b128 v[184:187], v151 offset:49152
	ds_read_b128 v[188:191], v151 offset:50176
	ds_read_b128 v[192:195], v151 offset:51200
	ds_read_b128 v[214:217], v151 offset:52224
	ds_read_b128 v[218:221], v151 offset:53248
	ds_read_b128 v[222:225], v151 offset:54272
	ds_read_b128 v[226:229], v151 offset:55296
	ds_read_b128 v[230:233], v151 offset:56320
	s_waitcnt vmcnt(8)
	s_cmp_lg_u32 s22, 0
	s_cbranch_scc1 .Lew_1812_30997
	s_waitcnt lgkmcnt(0)
.Lew_1812_30997:
	s_barrier
	s_setprio 1
	s_waitcnt lgkmcnt(0)
	v_mfma_f32_16x16x32_bf16 v[94:97], v[146:149], v[184:187], v[94:97]
	v_mfma_f32_16x16x32_bf16 v[88:91], v[160:163], v[184:187], v[88:91]
	v_mfma_f32_16x16x32_bf16 v[84:87], v[146:149], v[192:195], v[84:87]
	v_mfma_f32_16x16x32_bf16 v[80:83], v[160:163], v[192:195], v[80:83]
	v_mfma_f32_16x16x32_bf16 v[76:79], v[146:149], v[218:221], v[76:79]
	v_mfma_f32_16x16x32_bf16 v[72:75], v[160:163], v[218:221], v[72:75]
	v_mfma_f32_16x16x32_bf16 v[68:71], v[146:149], v[226:229], v[68:71]
	v_mfma_f32_16x16x32_bf16 v[64:67], v[160:163], v[226:229], v[64:67]
	v_mfma_f32_16x16x32_bf16 v[94:97], v[152:155], v[188:191], v[94:97]
	v_mfma_f32_16x16x32_bf16 v[88:91], v[164:167], v[188:191], v[88:91]
	v_mfma_f32_16x16x32_bf16 v[84:87], v[152:155], v[214:217], v[84:87]
	v_mfma_f32_16x16x32_bf16 v[80:83], v[164:167], v[214:217], v[80:83]
	v_mfma_f32_16x16x32_bf16 v[76:79], v[152:155], v[222:225], v[76:79]
	v_mfma_f32_16x16x32_bf16 v[72:75], v[164:167], v[222:225], v[72:75]
	v_mfma_f32_16x16x32_bf16 v[68:71], v[152:155], v[230:233], v[68:71]
	v_mfma_f32_16x16x32_bf16 v[64:67], v[164:167], v[230:233], v[64:67]
	s_setprio 0
	s_setprio 1
	v_mfma_f32_16x16x32_bf16 v[28:31], v[168:171], v[184:187], v[28:31]
	v_mfma_f32_16x16x32_bf16 v[24:27], v[176:179], v[184:187], v[24:27]
	v_mfma_f32_16x16x32_bf16 v[20:23], v[168:171], v[192:195], v[20:23]
	v_mfma_f32_16x16x32_bf16 v[16:19], v[176:179], v[192:195], v[16:19]
	v_mfma_f32_16x16x32_bf16 v[12:15], v[168:171], v[218:221], v[12:15]
	v_mfma_f32_16x16x32_bf16 v[8:11], v[176:179], v[218:221], v[8:11]
	v_mfma_f32_16x16x32_bf16 v[4:7], v[168:171], v[226:229], v[4:7]
	v_mfma_f32_16x16x32_bf16 v[0:3], v[176:179], v[226:229], v[0:3]
	v_mfma_f32_16x16x32_bf16 v[28:31], v[172:175], v[188:191], v[28:31]
	v_mfma_f32_16x16x32_bf16 v[24:27], v[180:183], v[188:191], v[24:27]
	v_mfma_f32_16x16x32_bf16 v[20:23], v[172:175], v[214:217], v[20:23]
	v_mfma_f32_16x16x32_bf16 v[16:19], v[180:183], v[214:217], v[16:19]
	v_mfma_f32_16x16x32_bf16 v[12:15], v[172:175], v[222:225], v[12:15]
	v_mfma_f32_16x16x32_bf16 v[8:11], v[180:183], v[222:225], v[8:11]
	v_mfma_f32_16x16x32_bf16 v[4:7], v[172:175], v[230:233], v[4:7]
	v_mfma_f32_16x16x32_bf16 v[0:3], v[180:183], v[230:233], v[0:3]
	s_setprio 0
	s_barrier
	s_add_u32 s6, s6, 0x100
	s_addc_u32 s7, s7, 0
	s_add_u32 s34, s34, 0x100
	s_addc_u32 s35, s35, 0
	s_cmp_ge_i32 s60, s44
	s_mov_b32 s30, s60
	s_cbranch_scc0 .LBB0_1812
